# v23
# speedup vs baseline: 1.0105x; 1.0037x over previous
.LBB0_269:
	s_add_u32 s26, s24, 0xfff80080
	s_addc_u32 s27, s25, -1
	s_add_i32 s70, 0, 0x10000
	v_add_u32_e32 v148, s70, v154
	ds_read_b128 v[150:153], v148
	ds_read_b128 v[158:161], v148 offset:1024
	ds_read_b128 v[162:165], v148 offset:2048
	ds_read_b128 v[166:169], v148 offset:3072
	s_cmp_eq_u32 s69, 28
	s_cselect_b32 s29, s7, s27
	s_cselect_b32 s28, s6, s26
	s_cselect_b32 s27, s23, s17
	s_cselect_b32 s26, s22, s5
	s_add_i32 m0, s58, 0xc000
	ds_read_b128 v[170:173], v156
	ds_read_b128 v[174:177], v156 offset:1024
	ds_read_b128 v[180:183], v156 offset:2048
	ds_read_b128 v[184:187], v156 offset:3072
	ds_read_b128 v[188:191], v156 offset:4096
	ds_read_b128 v[192:195], v156 offset:5120
	ds_read_b128 v[196:199], v156 offset:6144
	ds_read_b128 v[224:227], v156 offset:7168
	global_load_lds_dwordx4 v146, s[24:25]
	s_add_i32 m0, s58, 0xe000
	s_nop 0
	global_load_lds_dwordx4 v144, s[24:25]
	s_waitcnt lgkmcnt(8)
	s_barrier
	s_waitcnt lgkmcnt(0)
	s_waitcnt lgkmcnt(0)
	v_mfma_f32_16x16x32_bf16 v[124:127], v[150:153], v[170:173], v[124:127]
	v_mfma_f32_16x16x32_bf16 v[120:123], v[162:165], v[170:173], v[120:123]
	v_mfma_f32_16x16x32_bf16 v[108:111], v[150:153], v[180:183], v[108:111]
	v_mfma_f32_16x16x32_bf16 v[104:107], v[162:165], v[180:183], v[104:107]
	v_mfma_f32_16x16x32_bf16 v[92:95], v[150:153], v[188:191], v[92:95]
	v_mfma_f32_16x16x32_bf16 v[88:91], v[162:165], v[188:191], v[88:91]
	v_mfma_f32_16x16x32_bf16 v[76:79], v[150:153], v[196:199], v[76:79]
	v_mfma_f32_16x16x32_bf16 v[72:75], v[162:165], v[196:199], v[72:75]
	v_mfma_f32_16x16x32_bf16 v[124:127], v[158:161], v[174:177], v[124:127]
	v_mfma_f32_16x16x32_bf16 v[120:123], v[166:169], v[174:177], v[120:123]
	v_mfma_f32_16x16x32_bf16 v[108:111], v[158:161], v[184:187], v[108:111]
	v_mfma_f32_16x16x32_bf16 v[104:107], v[166:169], v[184:187], v[104:107]
	v_mfma_f32_16x16x32_bf16 v[92:95], v[158:161], v[192:195], v[92:95]
	v_mfma_f32_16x16x32_bf16 v[88:91], v[166:169], v[192:195], v[88:91]
	v_mfma_f32_16x16x32_bf16 v[76:79], v[158:161], v[224:227], v[76:79]
	v_mfma_f32_16x16x32_bf16 v[72:75], v[166:169], v[224:227], v[72:75]
	s_barrier
	s_add_i32 s72, 0, 0x14000
	s_add_i32 s70, s70, s57
	v_add_u32_e32 v148, s72, v154
	s_mov_b32 m0, s70
	ds_read_b128 v[228:231], v148
	ds_read_b128 v[232:235], v148 offset:1024
	ds_read_b128 v[236:239], v148 offset:2048
	ds_read_b128 v[240:243], v148 offset:3072
	global_load_lds_dwordx4 v130, s[26:27]
	s_add_i32 m0, s70, 0x2000
	s_nop 0
	global_load_lds_dwordx4 v134, s[26:27]
	s_barrier
	s_waitcnt lgkmcnt(0)
	s_waitcnt lgkmcnt(0)
	v_mfma_f32_16x16x32_bf16 v[116:119], v[228:231], v[170:173], v[116:119]
	v_mfma_f32_16x16x32_bf16 v[112:115], v[236:239], v[170:173], v[112:115]
	v_mfma_f32_16x16x32_bf16 v[100:103], v[228:231], v[180:183], v[100:103]
	v_mfma_f32_16x16x32_bf16 v[96:99], v[236:239], v[180:183], v[96:99]
	v_mfma_f32_16x16x32_bf16 v[84:87], v[228:231], v[188:191], v[84:87]
	v_mfma_f32_16x16x32_bf16 v[80:83], v[236:239], v[188:191], v[80:83]
	v_mfma_f32_16x16x32_bf16 v[68:71], v[228:231], v[196:199], v[68:71]
	v_mfma_f32_16x16x32_bf16 v[64:67], v[236:239], v[196:199], v[64:67]
	v_mfma_f32_16x16x32_bf16 v[116:119], v[232:235], v[174:177], v[116:119]
	v_mfma_f32_16x16x32_bf16 v[112:115], v[240:243], v[174:177], v[112:115]
	v_mfma_f32_16x16x32_bf16 v[100:103], v[232:235], v[184:187], v[100:103]
	v_mfma_f32_16x16x32_bf16 v[96:99], v[240:243], v[184:187], v[96:99]
	v_mfma_f32_16x16x32_bf16 v[84:87], v[232:235], v[192:195], v[84:87]
	v_mfma_f32_16x16x32_bf16 v[80:83], v[240:243], v[192:195], v[80:83]
	v_mfma_f32_16x16x32_bf16 v[68:71], v[232:235], v[224:227], v[68:71]
	v_mfma_f32_16x16x32_bf16 v[64:67], v[240:243], v[224:227], v[64:67]
	s_mov_b32 m0, s58
	s_mov_b64 s[100:101], s[28:29]
	s_barrier
	ds_read_b128 v[170:173], v156 offset:16384
	ds_read_b128 v[174:177], v156 offset:17408
	ds_read_b128 v[180:183], v156 offset:18432
	ds_read_b128 v[184:187], v156 offset:19456
	ds_read_b128 v[188:191], v156 offset:20480
	ds_read_b128 v[192:195], v156 offset:21504
	ds_read_b128 v[196:199], v156 offset:22528
	ds_read_b128 v[224:227], v156 offset:23552
	global_load_lds_dwordx4 v128, s[28:29]
	s_mov_b64 s[100:101], s[28:29]
	s_mov_b32 m0, s59
	s_nop 0
	global_load_lds_dwordx4 v132, s[28:29]
	s_barrier
	s_waitcnt lgkmcnt(0)
	s_waitcnt lgkmcnt(0)
	v_mfma_f32_16x16x32_bf16 v[60:63], v[150:153], v[170:173], v[60:63]
	v_mfma_f32_16x16x32_bf16 v[56:59], v[162:165], v[170:173], v[56:59]
	v_mfma_f32_16x16x32_bf16 v[44:47], v[150:153], v[180:183], v[44:47]
	v_mfma_f32_16x16x32_bf16 v[40:43], v[162:165], v[180:183], v[40:43]
	v_mfma_f32_16x16x32_bf16 v[28:31], v[150:153], v[188:191], v[28:31]
	v_mfma_f32_16x16x32_bf16 v[24:27], v[162:165], v[188:191], v[24:27]
	v_mfma_f32_16x16x32_bf16 v[12:15], v[150:153], v[196:199], v[12:15]
	v_mfma_f32_16x16x32_bf16 v[8:11], v[162:165], v[196:199], v[8:11]
	v_mfma_f32_16x16x32_bf16 v[60:63], v[158:161], v[174:177], v[60:63]
	v_mfma_f32_16x16x32_bf16 v[56:59], v[166:169], v[174:177], v[56:59]
	v_mfma_f32_16x16x32_bf16 v[44:47], v[158:161], v[184:187], v[44:47]
	v_mfma_f32_16x16x32_bf16 v[40:43], v[166:169], v[184:187], v[40:43]
	v_mfma_f32_16x16x32_bf16 v[28:31], v[158:161], v[192:195], v[28:31]
	v_mfma_f32_16x16x32_bf16 v[24:27], v[166:169], v[192:195], v[24:27]
	v_mfma_f32_16x16x32_bf16 v[12:15], v[158:161], v[224:227], v[12:15]
	v_mfma_f32_16x16x32_bf16 v[8:11], v[166:169], v[224:227], v[8:11]
	s_barrier
	s_add_u32 s70, s26, 0x80000
	s_addc_u32 s71, s27, 0
	s_add_i32 s72, s72, s57
	s_mov_b32 m0, s72
	s_nop 0
	global_load_lds_dwordx4 v130, s[70:71]
	s_add_i32 m0, s72, 0x2000
	s_nop 0
	global_load_lds_dwordx4 v134, s[70:71]
	s_waitcnt vmcnt(6)
	s_barrier
	v_mfma_f32_16x16x32_bf16 v[52:55], v[228:231], v[170:173], v[52:55]
	v_mfma_f32_16x16x32_bf16 v[48:51], v[236:239], v[170:173], v[48:51]
	v_mfma_f32_16x16x32_bf16 v[36:39], v[228:231], v[180:183], v[36:39]
	v_mfma_f32_16x16x32_bf16 v[32:35], v[236:239], v[180:183], v[32:35]
	v_mfma_f32_16x16x32_bf16 v[20:23], v[228:231], v[188:191], v[20:23]
	v_mfma_f32_16x16x32_bf16 v[16:19], v[236:239], v[188:191], v[16:19]
	v_mfma_f32_16x16x32_bf16 v[4:7], v[228:231], v[196:199], v[4:7]
	v_mfma_f32_16x16x32_bf16 v[0:3], v[236:239], v[196:199], v[0:3]
	v_mfma_f32_16x16x32_bf16 v[52:55], v[232:235], v[174:177], v[52:55]
	v_mfma_f32_16x16x32_bf16 v[48:51], v[240:243], v[174:177], v[48:51]
	v_mfma_f32_16x16x32_bf16 v[36:39], v[232:235], v[184:187], v[36:39]
	v_mfma_f32_16x16x32_bf16 v[32:35], v[240:243], v[184:187], v[32:35]
	v_mfma_f32_16x16x32_bf16 v[20:23], v[232:235], v[192:195], v[20:23]
	v_mfma_f32_16x16x32_bf16 v[16:19], v[240:243], v[192:195], v[16:19]
	v_mfma_f32_16x16x32_bf16 v[4:7], v[232:235], v[224:227], v[4:7]
	v_mfma_f32_16x16x32_bf16 v[0:3], v[240:243], v[224:227], v[0:3]
	s_add_i32 s70, 0, 0x18000
	v_add_u32_e32 v148, s70, v154
	s_barrier
	ds_read_b128 v[150:153], v148
	ds_read_b128 v[158:161], v148 offset:1024
	ds_read_b128 v[162:165], v148 offset:2048
	ds_read_b128 v[166:169], v148 offset:3072
	s_add_u32 s28, s28, 0x80000
	s_addc_u32 s29, s29, 0
	s_mov_b32 m0, s60
	ds_read_b128 v[170:173], v156 offset:32768
	ds_read_b128 v[174:177], v156 offset:33792
	ds_read_b128 v[180:183], v156 offset:34816
	ds_read_b128 v[184:187], v156 offset:35840
	ds_read_b128 v[188:191], v156 offset:36864
	ds_read_b128 v[192:195], v156 offset:37888
	ds_read_b128 v[196:199], v156 offset:38912
	ds_read_b128 v[224:227], v156 offset:39936
	global_load_lds_dwordx4 v128, s[28:29]
	s_mov_b32 m0, s61
	s_nop 0
	global_load_lds_dwordx4 v132, s[28:29]
	s_waitcnt lgkmcnt(8)
	s_barrier
	s_waitcnt lgkmcnt(0)
	s_waitcnt lgkmcnt(0)
	v_mfma_f32_16x16x32_bf16 v[124:127], v[150:153], v[170:173], v[124:127]
	v_mfma_f32_16x16x32_bf16 v[120:123], v[162:165], v[170:173], v[120:123]
	v_mfma_f32_16x16x32_bf16 v[108:111], v[150:153], v[180:183], v[108:111]
	v_mfma_f32_16x16x32_bf16 v[104:107], v[162:165], v[180:183], v[104:107]
	v_mfma_f32_16x16x32_bf16 v[92:95], v[150:153], v[188:191], v[92:95]
	v_mfma_f32_16x16x32_bf16 v[88:91], v[162:165], v[188:191], v[88:91]
	v_mfma_f32_16x16x32_bf16 v[76:79], v[150:153], v[196:199], v[76:79]
	v_mfma_f32_16x16x32_bf16 v[72:75], v[162:165], v[196:199], v[72:75]
	v_mfma_f32_16x16x32_bf16 v[124:127], v[158:161], v[174:177], v[124:127]
	v_mfma_f32_16x16x32_bf16 v[120:123], v[166:169], v[174:177], v[120:123]
	v_mfma_f32_16x16x32_bf16 v[108:111], v[158:161], v[184:187], v[108:111]
	v_mfma_f32_16x16x32_bf16 v[104:107], v[166:169], v[184:187], v[104:107]
	v_mfma_f32_16x16x32_bf16 v[92:95], v[158:161], v[192:195], v[92:95]
	v_mfma_f32_16x16x32_bf16 v[88:91], v[166:169], v[192:195], v[88:91]
	v_mfma_f32_16x16x32_bf16 v[76:79], v[158:161], v[224:227], v[76:79]
	v_mfma_f32_16x16x32_bf16 v[72:75], v[166:169], v[224:227], v[72:75]
	s_barrier
	s_add_i32 s28, 0, 0x1c000
	s_add_i32 s29, s70, s57
	v_add_u32_e32 v148, s28, v154
	s_add_i32 m0, s29, 0xffffff80
	ds_read_b128 v[228:231], v148
	ds_read_b128 v[232:235], v148 offset:1024
	ds_read_b128 v[236:239], v148 offset:2048
	ds_read_b128 v[240:243], v148 offset:3072
	global_load_lds_dwordx4 v130, s[26:27] offset:128
	s_add_i32 m0, s29, 0x1f80
	s_nop 0
	global_load_lds_dwordx4 v134, s[26:27] offset:128
	s_barrier
	s_waitcnt lgkmcnt(0)
	s_waitcnt lgkmcnt(0)
	v_mfma_f32_16x16x32_bf16 v[116:119], v[228:231], v[170:173], v[116:119]
	v_mfma_f32_16x16x32_bf16 v[112:115], v[236:239], v[170:173], v[112:115]
	v_mfma_f32_16x16x32_bf16 v[100:103], v[228:231], v[180:183], v[100:103]
	v_mfma_f32_16x16x32_bf16 v[96:99], v[236:239], v[180:183], v[96:99]
	v_mfma_f32_16x16x32_bf16 v[84:87], v[228:231], v[188:191], v[84:87]
	v_mfma_f32_16x16x32_bf16 v[80:83], v[236:239], v[188:191], v[80:83]
	v_mfma_f32_16x16x32_bf16 v[68:71], v[228:231], v[196:199], v[68:71]
	v_mfma_f32_16x16x32_bf16 v[64:67], v[236:239], v[196:199], v[64:67]
	v_mfma_f32_16x16x32_bf16 v[116:119], v[232:235], v[174:177], v[116:119]
	v_mfma_f32_16x16x32_bf16 v[112:115], v[240:243], v[174:177], v[112:115]
	v_mfma_f32_16x16x32_bf16 v[100:103], v[232:235], v[184:187], v[100:103]
	v_mfma_f32_16x16x32_bf16 v[96:99], v[240:243], v[184:187], v[96:99]
	v_mfma_f32_16x16x32_bf16 v[84:87], v[232:235], v[192:195], v[84:87]
	v_mfma_f32_16x16x32_bf16 v[80:83], v[240:243], v[192:195], v[80:83]
	v_mfma_f32_16x16x32_bf16 v[68:71], v[232:235], v[224:227], v[68:71]
	v_mfma_f32_16x16x32_bf16 v[64:67], v[240:243], v[224:227], v[64:67]
	s_add_i32 m0, s62, 0xffffff80
	s_barrier
	ds_read_b128 v[170:173], v156 offset:49152
	ds_read_b128 v[174:177], v156 offset:50176
	ds_read_b128 v[180:183], v156 offset:51200
	ds_read_b128 v[184:187], v156 offset:52224
	ds_read_b128 v[188:191], v156 offset:53248
	ds_read_b128 v[192:195], v156 offset:54272
	ds_read_b128 v[196:199], v156 offset:55296
	ds_read_b128 v[224:227], v156 offset:56320
	global_load_lds_dwordx4 v128, s[100:101] offset:128
	s_add_i32 m0, s63, 0xffffff80
	s_nop 0
	global_load_lds_dwordx4 v132, s[100:101] offset:128
	s_barrier
	s_waitcnt lgkmcnt(0)
	s_waitcnt lgkmcnt(0)
	v_mfma_f32_16x16x32_bf16 v[60:63], v[150:153], v[170:173], v[60:63]
	v_mfma_f32_16x16x32_bf16 v[56:59], v[162:165], v[170:173], v[56:59]
	v_mfma_f32_16x16x32_bf16 v[44:47], v[150:153], v[180:183], v[44:47]
	v_mfma_f32_16x16x32_bf16 v[40:43], v[162:165], v[180:183], v[40:43]
	v_mfma_f32_16x16x32_bf16 v[28:31], v[150:153], v[188:191], v[28:31]
	v_mfma_f32_16x16x32_bf16 v[24:27], v[162:165], v[188:191], v[24:27]
	v_mfma_f32_16x16x32_bf16 v[12:15], v[150:153], v[196:199], v[12:15]
	v_mfma_f32_16x16x32_bf16 v[8:11], v[162:165], v[196:199], v[8:11]
	v_mfma_f32_16x16x32_bf16 v[60:63], v[158:161], v[174:177], v[60:63]
	v_mfma_f32_16x16x32_bf16 v[56:59], v[166:169], v[174:177], v[56:59]
	v_mfma_f32_16x16x32_bf16 v[44:47], v[158:161], v[184:187], v[44:47]
	v_mfma_f32_16x16x32_bf16 v[40:43], v[166:169], v[184:187], v[40:43]
	v_mfma_f32_16x16x32_bf16 v[28:31], v[158:161], v[192:195], v[28:31]
	v_mfma_f32_16x16x32_bf16 v[24:27], v[166:169], v[192:195], v[24:27]
	v_mfma_f32_16x16x32_bf16 v[12:15], v[158:161], v[224:227], v[12:15]
	v_mfma_f32_16x16x32_bf16 v[8:11], v[166:169], v[224:227], v[8:11]
	s_barrier
	s_add_u32 s26, s26, 0x80080
	s_addc_u32 s27, s27, 0
	s_add_i32 s28, s28, s57
	s_mov_b32 m0, s28
	s_nop 0
	global_load_lds_dwordx4 v130, s[26:27]
	s_add_i32 m0, s28, 0x2000
	s_nop 0
	global_load_lds_dwordx4 v134, s[26:27]
	s_waitcnt vmcnt(6)
	s_barrier
	v_mfma_f32_16x16x32_bf16 v[52:55], v[228:231], v[170:173], v[52:55]
	v_mfma_f32_16x16x32_bf16 v[48:51], v[236:239], v[170:173], v[48:51]
	v_mfma_f32_16x16x32_bf16 v[36:39], v[228:231], v[180:183], v[36:39]
	v_mfma_f32_16x16x32_bf16 v[32:35], v[236:239], v[180:183], v[32:35]
	v_mfma_f32_16x16x32_bf16 v[20:23], v[228:231], v[188:191], v[20:23]
	v_mfma_f32_16x16x32_bf16 v[16:19], v[236:239], v[188:191], v[16:19]
	v_mfma_f32_16x16x32_bf16 v[4:7], v[228:231], v[196:199], v[4:7]
	v_mfma_f32_16x16x32_bf16 v[0:3], v[236:239], v[196:199], v[0:3]
	v_mfma_f32_16x16x32_bf16 v[52:55], v[232:235], v[174:177], v[52:55]
	v_mfma_f32_16x16x32_bf16 v[48:51], v[240:243], v[174:177], v[48:51]
	v_mfma_f32_16x16x32_bf16 v[36:39], v[232:235], v[184:187], v[36:39]
	v_mfma_f32_16x16x32_bf16 v[32:35], v[240:243], v[184:187], v[32:35]
	v_mfma_f32_16x16x32_bf16 v[20:23], v[232:235], v[192:195], v[20:23]
	v_mfma_f32_16x16x32_bf16 v[16:19], v[240:243], v[192:195], v[16:19]
	v_mfma_f32_16x16x32_bf16 v[4:7], v[232:235], v[224:227], v[4:7]
	v_mfma_f32_16x16x32_bf16 v[0:3], v[240:243], v[224:227], v[0:3]
	s_add_i32 s69, s69, 2
	s_add_u32 s5, s5, 0x100
	s_addc_u32 s17, s17, 0
	s_add_u32 s24, s24, 0x100
	s_addc_u32 s25, s25, 0
	s_cmp_gt_u32 s69, 29
	s_barrier
	s_cbranch_scc0 .LBB0_269
	s_lshl_b32 s5, s68, 8
	v_lshl_add_u32 v158, s4, 8, v137
	v_or_b32_e32 v148, s5, v136
	s_addk_i32 s5, 0xf000
	s_lshr_b32 s4, s5, 2
	v_and_b32_e32 v159, 0xffffff80, v158
	s_and_b32 s22, s4, 0x3ffffe00
	v_add_u32_e32 v160, v159, v155
	v_add_u32_e32 v150, s22, v160
	s_lshl_b32 s17, s68, 9
	v_ashrrev_i32_e32 v151, 31, v150
	v_lshlrev_b64 v[152:153], 13, v[150:151]
	v_add_u32_e32 v150, s17, v160
	v_ashrrev_i32_e32 v151, 31, v150
	v_cmp_ne_u32_e64 s[6:7], 0, v149
	s_movk_i32 s4, 0xfff
	v_lshlrev_b64 v[150:151], 10, v[150:151]
	s_and_b64 vcc, exec, s[6:7]
	v_cmp_lt_i32_e64 s[4:5], s4, v148
	v_cvt_pk_bf16_f32 v124, v124, v125
	v_cvt_pk_bf16_f32 v125, v126, v127
	v_cvt_pk_bf16_f32 v126, v120, v121
	v_cvt_pk_bf16_f32 v127, v122, v123
	s_cbranch_vccz .LBB0_290
	s_and_saveexec_b64 s[24:25], s[4:5]
	s_xor_b64 s[4:5], exec, s[24:25]
	v_and_b32_e32 v122, 0x778, v148
	v_lshl_add_u64 v[120:121], v[138:139], 0, v[152:153]
	v_lshlrev_b32_e32 v178, 1, v122
	v_lshl_add_u64 v[122:123], v[120:121], 0, v[178:179]
	s_andn2_saveexec_b64 s[4:5], s[4:5]
	v_lshl_add_u64 v[122:123], v[142:143], 0, v[150:151]
	s_or_b64 exec, exec, s[4:5]
	s_movk_i32 s4, 0x1a00
	v_mad_i64_i32 v[120:121], s[4:5], v158, s4, 0
	s_cbranch_execnz .LBB0_277

.LBB0_935:
	s_add_u32 s12, s10, 0xf4c00080
	s_addc_u32 s13, s11, -1
	s_cmp_lg_u32 s28, 60
	s_cselect_b32 s12, s12, 0
	s_cselect_b32 s13, s13, 0
	s_add_u32 s14, s6, s12
	s_addc_u32 s15, s7, s13
	s_add_i32 s29, 0, 0x10000
	v_add_u32_e32 v150, s29, v140
	ds_read_b128 v[142:145], v150
	ds_read_b128 v[146:149], v150 offset:1024
	ds_read_b128 v[154:157], v150 offset:2048
	ds_read_b128 v[158:161], v150 offset:3072
	s_add_u32 s12, s8, s12
	s_addc_u32 s13, s9, s13
	v_lshl_add_u64 v[150:151], v[136:137], 0, s[10:11]
	s_add_i32 m0, s22, 0xc000
	ds_read_b128 v[162:165], v141
	ds_read_b128 v[166:169], v141 offset:1024
	ds_read_b128 v[170:173], v141 offset:2048
	ds_read_b128 v[174:177], v141 offset:3072
	ds_read_b128 v[180:183], v141 offset:4096
	ds_read_b128 v[184:187], v141 offset:5120
	ds_read_b128 v[188:191], v141 offset:6144
	ds_read_b128 v[192:195], v141 offset:7168
	global_load_lds_dwordx4 v[150:151], off
	v_lshl_add_u64 v[150:151], v[134:135], 0, s[10:11]
	s_add_i32 m0, s22, 0xe000
	s_nop 0
	global_load_lds_dwordx4 v[150:151], off
	s_waitcnt lgkmcnt(8)
	s_barrier
	s_waitcnt lgkmcnt(0)
	s_waitcnt lgkmcnt(0)
	v_mfma_f32_16x16x32_bf16 v[124:127], v[142:145], v[162:165], v[124:127]
	v_mfma_f32_16x16x32_bf16 v[120:123], v[154:157], v[162:165], v[120:123]
	v_mfma_f32_16x16x32_bf16 v[116:119], v[142:145], v[170:173], v[116:119]
	v_mfma_f32_16x16x32_bf16 v[108:111], v[154:157], v[170:173], v[108:111]
	v_mfma_f32_16x16x32_bf16 v[100:103], v[142:145], v[180:183], v[100:103]
	v_mfma_f32_16x16x32_bf16 v[92:95], v[154:157], v[180:183], v[92:95]
	v_mfma_f32_16x16x32_bf16 v[84:87], v[142:145], v[188:191], v[84:87]
	v_mfma_f32_16x16x32_bf16 v[76:79], v[154:157], v[188:191], v[76:79]
	v_mfma_f32_16x16x32_bf16 v[124:127], v[146:149], v[166:169], v[124:127]
	v_mfma_f32_16x16x32_bf16 v[120:123], v[158:161], v[166:169], v[120:123]
	v_mfma_f32_16x16x32_bf16 v[116:119], v[146:149], v[174:177], v[116:119]
	v_mfma_f32_16x16x32_bf16 v[108:111], v[158:161], v[174:177], v[108:111]
	v_mfma_f32_16x16x32_bf16 v[100:103], v[146:149], v[184:187], v[100:103]
	v_mfma_f32_16x16x32_bf16 v[92:95], v[158:161], v[184:187], v[92:95]
	v_mfma_f32_16x16x32_bf16 v[84:87], v[146:149], v[192:195], v[84:87]
	v_mfma_f32_16x16x32_bf16 v[76:79], v[158:161], v[192:195], v[76:79]
	s_barrier
	s_add_i32 s35, 0, 0x14000
	v_add_u32_e32 v150, s35, v140
	s_add_i32 s29, s29, s16
	ds_read_b128 v[196:199], v150
	ds_read_b128 v[224:227], v150 offset:1024
	ds_read_b128 v[228:231], v150 offset:2048
	ds_read_b128 v[232:235], v150 offset:3072
	s_mov_b32 m0, s29
	global_load_lds_dwordx4 v178, s[12:13]
	s_add_i32 m0, s29, 0x2000
	s_nop 0
	global_load_lds_dwordx4 v128, s[12:13]
	s_barrier
	s_waitcnt lgkmcnt(0)
	s_waitcnt lgkmcnt(0)
	v_mfma_f32_16x16x32_bf16 v[112:115], v[196:199], v[162:165], v[112:115]
	v_mfma_f32_16x16x32_bf16 v[104:107], v[228:231], v[162:165], v[104:107]
	v_mfma_f32_16x16x32_bf16 v[96:99], v[196:199], v[170:173], v[96:99]
	v_mfma_f32_16x16x32_bf16 v[88:91], v[228:231], v[170:173], v[88:91]
	v_mfma_f32_16x16x32_bf16 v[80:83], v[196:199], v[180:183], v[80:83]
	v_mfma_f32_16x16x32_bf16 v[72:75], v[228:231], v[180:183], v[72:75]
	v_mfma_f32_16x16x32_bf16 v[68:71], v[196:199], v[188:191], v[68:71]
	v_mfma_f32_16x16x32_bf16 v[64:67], v[228:231], v[188:191], v[64:67]
	v_mfma_f32_16x16x32_bf16 v[112:115], v[224:227], v[166:169], v[112:115]
	v_mfma_f32_16x16x32_bf16 v[104:107], v[232:235], v[166:169], v[104:107]
	v_mfma_f32_16x16x32_bf16 v[96:99], v[224:227], v[174:177], v[96:99]
	v_mfma_f32_16x16x32_bf16 v[88:91], v[232:235], v[174:177], v[88:91]
	v_mfma_f32_16x16x32_bf16 v[80:83], v[224:227], v[184:187], v[80:83]
	v_mfma_f32_16x16x32_bf16 v[72:75], v[232:235], v[184:187], v[72:75]
	v_mfma_f32_16x16x32_bf16 v[68:71], v[224:227], v[192:195], v[68:71]
	v_mfma_f32_16x16x32_bf16 v[64:67], v[232:235], v[192:195], v[64:67]
	s_mov_b32 m0, s22
	s_mov_b64 s[100:101], s[14:15]
	s_barrier
	ds_read_b128 v[162:165], v141 offset:16384
	ds_read_b128 v[166:169], v141 offset:17408
	ds_read_b128 v[170:173], v141 offset:18432
	ds_read_b128 v[174:177], v141 offset:19456
	ds_read_b128 v[180:183], v141 offset:20480
	ds_read_b128 v[184:187], v141 offset:21504
	ds_read_b128 v[188:191], v141 offset:22528
	ds_read_b128 v[192:195], v141 offset:23552
	global_load_lds_dwordx4 v132, s[14:15]
	s_mov_b64 s[100:101], s[14:15]
	s_mov_b32 m0, s23
	s_nop 0
	global_load_lds_dwordx4 v130, s[14:15]
	s_barrier
	s_waitcnt lgkmcnt(0)
	s_waitcnt lgkmcnt(0)
	v_mfma_f32_16x16x32_bf16 v[60:63], v[142:145], v[162:165], v[60:63]
	v_mfma_f32_16x16x32_bf16 v[56:59], v[154:157], v[162:165], v[56:59]
	v_mfma_f32_16x16x32_bf16 v[52:55], v[142:145], v[170:173], v[52:55]
	v_mfma_f32_16x16x32_bf16 v[44:47], v[154:157], v[170:173], v[44:47]
	v_mfma_f32_16x16x32_bf16 v[36:39], v[142:145], v[180:183], v[36:39]
	v_mfma_f32_16x16x32_bf16 v[28:31], v[154:157], v[180:183], v[28:31]
	v_mfma_f32_16x16x32_bf16 v[20:23], v[142:145], v[188:191], v[20:23]
	v_mfma_f32_16x16x32_bf16 v[12:15], v[154:157], v[188:191], v[12:15]
	v_mfma_f32_16x16x32_bf16 v[60:63], v[146:149], v[166:169], v[60:63]
	v_mfma_f32_16x16x32_bf16 v[56:59], v[158:161], v[166:169], v[56:59]
	v_mfma_f32_16x16x32_bf16 v[52:55], v[146:149], v[174:177], v[52:55]
	v_mfma_f32_16x16x32_bf16 v[44:47], v[158:161], v[174:177], v[44:47]
	v_mfma_f32_16x16x32_bf16 v[36:39], v[146:149], v[184:187], v[36:39]
	v_mfma_f32_16x16x32_bf16 v[28:31], v[158:161], v[184:187], v[28:31]
	v_mfma_f32_16x16x32_bf16 v[20:23], v[146:149], v[192:195], v[20:23]
	v_mfma_f32_16x16x32_bf16 v[12:15], v[158:161], v[192:195], v[12:15]
	s_barrier
	s_add_u32 s30, s12, 0x100000
	s_addc_u32 s31, s13, 0
	s_add_i32 s29, s35, s16
	s_mov_b32 m0, s29
	s_nop 0
	global_load_lds_dwordx4 v178, s[30:31]
	s_add_i32 m0, s29, 0x2000
	s_nop 0
	global_load_lds_dwordx4 v128, s[30:31]
	s_waitcnt vmcnt(6)
	s_barrier
	v_mfma_f32_16x16x32_bf16 v[48:51], v[196:199], v[162:165], v[48:51]
	v_mfma_f32_16x16x32_bf16 v[40:43], v[228:231], v[162:165], v[40:43]
	v_mfma_f32_16x16x32_bf16 v[32:35], v[196:199], v[170:173], v[32:35]
	v_mfma_f32_16x16x32_bf16 v[24:27], v[228:231], v[170:173], v[24:27]
	v_mfma_f32_16x16x32_bf16 v[16:19], v[196:199], v[180:183], v[16:19]
	v_mfma_f32_16x16x32_bf16 v[8:11], v[228:231], v[180:183], v[8:11]
	v_mfma_f32_16x16x32_bf16 v[4:7], v[196:199], v[188:191], v[4:7]
	v_mfma_f32_16x16x32_bf16 v[0:3], v[228:231], v[188:191], v[0:3]
	v_mfma_f32_16x16x32_bf16 v[48:51], v[224:227], v[166:169], v[48:51]
	v_mfma_f32_16x16x32_bf16 v[40:43], v[232:235], v[166:169], v[40:43]
	v_mfma_f32_16x16x32_bf16 v[32:35], v[224:227], v[174:177], v[32:35]
	v_mfma_f32_16x16x32_bf16 v[24:27], v[232:235], v[174:177], v[24:27]
	v_mfma_f32_16x16x32_bf16 v[16:19], v[224:227], v[184:187], v[16:19]
	v_mfma_f32_16x16x32_bf16 v[8:11], v[232:235], v[184:187], v[8:11]
	v_mfma_f32_16x16x32_bf16 v[4:7], v[224:227], v[192:195], v[4:7]
	v_mfma_f32_16x16x32_bf16 v[0:3], v[232:235], v[192:195], v[0:3]
	s_add_i32 s29, 0, 0x18000
	v_add_u32_e32 v153, s29, v140
	s_barrier
	ds_read_b128 v[142:145], v153
	ds_read_b128 v[146:149], v153 offset:1024
	ds_read_b128 v[154:157], v153 offset:2048
	ds_read_b128 v[158:161], v153 offset:3072
	s_add_u32 s14, s14, 0x100000
	s_addc_u32 s15, s15, 0
	s_mov_b32 m0, s24
	ds_read_b128 v[162:165], v141 offset:32768
	ds_read_b128 v[166:169], v141 offset:33792
	ds_read_b128 v[170:173], v141 offset:34816
	ds_read_b128 v[174:177], v141 offset:35840
	ds_read_b128 v[180:183], v141 offset:36864
	ds_read_b128 v[184:187], v141 offset:37888
	ds_read_b128 v[188:191], v141 offset:38912
	ds_read_b128 v[192:195], v141 offset:39936
	global_load_lds_dwordx4 v132, s[14:15]
	s_mov_b32 m0, s25
	s_nop 0
	global_load_lds_dwordx4 v130, s[14:15]
	s_waitcnt lgkmcnt(8)
	s_barrier
	s_waitcnt lgkmcnt(0)
	s_waitcnt lgkmcnt(0)
	v_mfma_f32_16x16x32_bf16 v[124:127], v[142:145], v[162:165], v[124:127]
	v_mfma_f32_16x16x32_bf16 v[120:123], v[154:157], v[162:165], v[120:123]
	v_mfma_f32_16x16x32_bf16 v[116:119], v[142:145], v[170:173], v[116:119]
	v_mfma_f32_16x16x32_bf16 v[108:111], v[154:157], v[170:173], v[108:111]
	v_mfma_f32_16x16x32_bf16 v[100:103], v[142:145], v[180:183], v[100:103]
	v_mfma_f32_16x16x32_bf16 v[92:95], v[154:157], v[180:183], v[92:95]
	v_mfma_f32_16x16x32_bf16 v[84:87], v[142:145], v[188:191], v[84:87]
	v_mfma_f32_16x16x32_bf16 v[76:79], v[154:157], v[188:191], v[76:79]
	v_mfma_f32_16x16x32_bf16 v[124:127], v[146:149], v[166:169], v[124:127]
	v_mfma_f32_16x16x32_bf16 v[120:123], v[158:161], v[166:169], v[120:123]
	v_mfma_f32_16x16x32_bf16 v[116:119], v[146:149], v[174:177], v[116:119]
	v_mfma_f32_16x16x32_bf16 v[108:111], v[158:161], v[174:177], v[108:111]
	v_mfma_f32_16x16x32_bf16 v[100:103], v[146:149], v[184:187], v[100:103]
	v_mfma_f32_16x16x32_bf16 v[92:95], v[158:161], v[184:187], v[92:95]
	v_mfma_f32_16x16x32_bf16 v[84:87], v[146:149], v[192:195], v[84:87]
	v_mfma_f32_16x16x32_bf16 v[76:79], v[158:161], v[192:195], v[76:79]
	s_barrier
	s_add_i32 s14, 0, 0x1c000
	s_add_i32 s15, s29, s16
	v_add_u32_e32 v153, s14, v140
	s_add_i32 m0, s15, 0xffffff80
	ds_read_b128 v[196:199], v153
	ds_read_b128 v[224:227], v153 offset:1024
	ds_read_b128 v[228:231], v153 offset:2048
	ds_read_b128 v[232:235], v153 offset:3072
	global_load_lds_dwordx4 v178, s[12:13] offset:128
	s_add_i32 m0, s15, 0x1f80
	s_nop 0
	global_load_lds_dwordx4 v128, s[12:13] offset:128
	s_barrier
	s_waitcnt lgkmcnt(0)
	s_waitcnt lgkmcnt(0)
	v_mfma_f32_16x16x32_bf16 v[112:115], v[196:199], v[162:165], v[112:115]
	v_mfma_f32_16x16x32_bf16 v[104:107], v[228:231], v[162:165], v[104:107]
	v_mfma_f32_16x16x32_bf16 v[96:99], v[196:199], v[170:173], v[96:99]
	v_mfma_f32_16x16x32_bf16 v[88:91], v[228:231], v[170:173], v[88:91]
	v_mfma_f32_16x16x32_bf16 v[80:83], v[196:199], v[180:183], v[80:83]
	v_mfma_f32_16x16x32_bf16 v[72:75], v[228:231], v[180:183], v[72:75]
	v_mfma_f32_16x16x32_bf16 v[68:71], v[196:199], v[188:191], v[68:71]
	v_mfma_f32_16x16x32_bf16 v[64:67], v[228:231], v[188:191], v[64:67]
	v_mfma_f32_16x16x32_bf16 v[112:115], v[224:227], v[166:169], v[112:115]
	v_mfma_f32_16x16x32_bf16 v[104:107], v[232:235], v[166:169], v[104:107]
	v_mfma_f32_16x16x32_bf16 v[96:99], v[224:227], v[174:177], v[96:99]
	v_mfma_f32_16x16x32_bf16 v[88:91], v[232:235], v[174:177], v[88:91]
	v_mfma_f32_16x16x32_bf16 v[80:83], v[224:227], v[184:187], v[80:83]
	v_mfma_f32_16x16x32_bf16 v[72:75], v[232:235], v[184:187], v[72:75]
	v_mfma_f32_16x16x32_bf16 v[68:71], v[224:227], v[192:195], v[68:71]
	v_mfma_f32_16x16x32_bf16 v[64:67], v[232:235], v[192:195], v[64:67]
	s_add_i32 m0, s26, 0xffffff80
	s_barrier
	ds_read_b128 v[162:165], v141 offset:49152
	ds_read_b128 v[166:169], v141 offset:50176
	ds_read_b128 v[170:173], v141 offset:51200
	ds_read_b128 v[174:177], v141 offset:52224
	ds_read_b128 v[180:183], v141 offset:53248
	ds_read_b128 v[184:187], v141 offset:54272
	ds_read_b128 v[188:191], v141 offset:55296
	ds_read_b128 v[192:195], v141 offset:56320
	global_load_lds_dwordx4 v132, s[100:101] offset:128
	s_add_i32 m0, s27, 0xffffff80
	s_nop 0
	global_load_lds_dwordx4 v130, s[100:101] offset:128
	s_barrier
	s_waitcnt lgkmcnt(0)
	s_waitcnt lgkmcnt(0)
	v_mfma_f32_16x16x32_bf16 v[60:63], v[142:145], v[162:165], v[60:63]
	v_mfma_f32_16x16x32_bf16 v[56:59], v[154:157], v[162:165], v[56:59]
	v_mfma_f32_16x16x32_bf16 v[52:55], v[142:145], v[170:173], v[52:55]
	v_mfma_f32_16x16x32_bf16 v[44:47], v[154:157], v[170:173], v[44:47]
	v_mfma_f32_16x16x32_bf16 v[36:39], v[142:145], v[180:183], v[36:39]
	v_mfma_f32_16x16x32_bf16 v[28:31], v[154:157], v[180:183], v[28:31]
	v_mfma_f32_16x16x32_bf16 v[20:23], v[142:145], v[188:191], v[20:23]
	v_mfma_f32_16x16x32_bf16 v[12:15], v[154:157], v[188:191], v[12:15]
	v_mfma_f32_16x16x32_bf16 v[60:63], v[146:149], v[166:169], v[60:63]
	v_mfma_f32_16x16x32_bf16 v[56:59], v[158:161], v[166:169], v[56:59]
	v_mfma_f32_16x16x32_bf16 v[52:55], v[146:149], v[174:177], v[52:55]
	v_mfma_f32_16x16x32_bf16 v[44:47], v[158:161], v[174:177], v[44:47]
	v_mfma_f32_16x16x32_bf16 v[36:39], v[146:149], v[184:187], v[36:39]
	v_mfma_f32_16x16x32_bf16 v[28:31], v[158:161], v[184:187], v[28:31]
	v_mfma_f32_16x16x32_bf16 v[20:23], v[146:149], v[192:195], v[20:23]
	v_mfma_f32_16x16x32_bf16 v[12:15], v[158:161], v[192:195], v[12:15]
	s_barrier
	s_add_u32 s12, s12, 0x100080
	s_addc_u32 s13, s13, 0
	s_add_i32 s14, s14, s16
	s_mov_b32 m0, s14
	s_nop 0
	global_load_lds_dwordx4 v178, s[12:13]
	s_add_i32 m0, s14, 0x2000
	s_nop 0
	global_load_lds_dwordx4 v128, s[12:13]
	s_waitcnt vmcnt(6)
	s_barrier
	v_mfma_f32_16x16x32_bf16 v[48:51], v[196:199], v[162:165], v[48:51]
	v_mfma_f32_16x16x32_bf16 v[40:43], v[228:231], v[162:165], v[40:43]
	v_mfma_f32_16x16x32_bf16 v[32:35], v[196:199], v[170:173], v[32:35]
	v_mfma_f32_16x16x32_bf16 v[24:27], v[228:231], v[170:173], v[24:27]
	v_mfma_f32_16x16x32_bf16 v[16:19], v[196:199], v[180:183], v[16:19]
	v_mfma_f32_16x16x32_bf16 v[8:11], v[228:231], v[180:183], v[8:11]
	v_mfma_f32_16x16x32_bf16 v[4:7], v[196:199], v[188:191], v[4:7]
	v_mfma_f32_16x16x32_bf16 v[0:3], v[228:231], v[188:191], v[0:3]
	v_mfma_f32_16x16x32_bf16 v[48:51], v[224:227], v[166:169], v[48:51]
	v_mfma_f32_16x16x32_bf16 v[40:43], v[232:235], v[166:169], v[40:43]
	v_mfma_f32_16x16x32_bf16 v[32:35], v[224:227], v[174:177], v[32:35]
	v_mfma_f32_16x16x32_bf16 v[24:27], v[232:235], v[174:177], v[24:27]
	v_mfma_f32_16x16x32_bf16 v[16:19], v[224:227], v[184:187], v[16:19]
	v_mfma_f32_16x16x32_bf16 v[8:11], v[232:235], v[184:187], v[8:11]
	v_mfma_f32_16x16x32_bf16 v[4:7], v[224:227], v[192:195], v[4:7]
	v_mfma_f32_16x16x32_bf16 v[0:3], v[232:235], v[192:195], v[0:3]
	s_add_i32 s28, s28, 2
	s_add_u32 s10, s10, 0x100
	s_addc_u32 s11, s11, 0
	s_cmp_gt_u32 s28, 61
	s_barrier
	s_cbranch_scc0 .LBB0_935
	v_readlane_b32 s6, v253, 51
	s_or_b32 s6, s17, s6
	v_cvt_pk_bf16_f32 v124, v124, v125
	v_cvt_pk_bf16_f32 v125, v126, v127
	v_cvt_pk_bf16_f32 v126, v120, v121
	v_cvt_pk_bf16_f32 v127, v122, v123
	s_nop 0
	v_or_b32_e32 v130, s6, v139
	v_readlane_b32 s6, v253, 44
	v_lshlrev_b32_e32 v178, 1, v130
	s_nop 0
	v_add_u32_e32 v131, s6, v138
	v_add_u32_e32 v128, 0x1000, v131
	v_ashrrev_i32_e32 v129, 31, v128
	v_lshlrev_b64 v[128:129], 12, v[128:129]
	v_lshl_add_u64 v[128:129], s[4:5], 0, v[128:129]
	v_lshl_add_u64 v[128:129], v[128:129], 0, v[178:179]
	global_store_dwordx4 v[128:129], v[124:127], off
	v_cvt_pk_bf16_f32 v112, v112, v113
	v_cvt_pk_bf16_f32 v113, v114, v115
	v_cvt_pk_bf16_f32 v114, v104, v105
	v_add_u32_e32 v104, 0x1010, v131
	v_ashrrev_i32_e32 v105, 31, v104
	v_lshlrev_b64 v[104:105], 12, v[104:105]
	v_lshl_add_u64 v[104:105], s[4:5], 0, v[104:105]
	v_cvt_pk_bf16_f32 v115, v106, v107
	global_store_dwordx4 v[128:129], v[112:115], off offset:256
	v_readlane_b32 s6, v255, 8
	s_nop 0
	v_lshl_add_u64 v[112:113], v[104:105], 0, v[178:179]
	v_cvt_pk_bf16_f32 v104, v116, v117
	v_cvt_pk_bf16_f32 v105, v118, v119
	v_cvt_pk_bf16_f32 v106, v108, v109
	v_cvt_pk_bf16_f32 v107, v110, v111
	global_store_dwordx4 v[112:113], v[104:107], off
	v_cvt_pk_bf16_f32 v96, v96, v97
	v_cvt_pk_bf16_f32 v97, v98, v99
	v_cvt_pk_bf16_f32 v98, v88, v89
	v_add_u32_e32 v88, 0x1020, v131
	v_ashrrev_i32_e32 v89, 31, v88
	v_lshlrev_b64 v[88:89], 12, v[88:89]
	v_lshl_add_u64 v[88:89], s[4:5], 0, v[88:89]
	v_cvt_pk_bf16_f32 v99, v90, v91
	global_store_dwordx4 v[112:113], v[96:99], off offset:256
	s_nop 1
	v_lshl_add_u64 v[96:97], v[88:89], 0, v[178:179]
	v_cvt_pk_bf16_f32 v88, v100, v101
	v_cvt_pk_bf16_f32 v89, v102, v103
	v_cvt_pk_bf16_f32 v90, v92, v93
	v_cvt_pk_bf16_f32 v91, v94, v95
	global_store_dwordx4 v[96:97], v[88:91], off
	v_cvt_pk_bf16_f32 v80, v80, v81
	v_cvt_pk_bf16_f32 v81, v82, v83
	v_cvt_pk_bf16_f32 v82, v72, v73
	v_add_u32_e32 v72, 0x1030, v131
	v_ashrrev_i32_e32 v73, 31, v72
	v_lshlrev_b64 v[72:73], 12, v[72:73]
	v_lshl_add_u64 v[72:73], s[4:5], 0, v[72:73]
	v_cvt_pk_bf16_f32 v83, v74, v75
	global_store_dwordx4 v[96:97], v[80:83], off offset:256
	s_nop 1
	v_lshl_add_u64 v[80:81], v[72:73], 0, v[178:179]
	v_cvt_pk_bf16_f32 v72, v84, v85
	v_cvt_pk_bf16_f32 v73, v86, v87
	v_cvt_pk_bf16_f32 v74, v76, v77
	v_cvt_pk_bf16_f32 v75, v78, v79
	global_store_dwordx4 v[80:81], v[72:75], off
	v_cvt_pk_bf16_f32 v68, v68, v69
	v_cvt_pk_bf16_f32 v69, v70, v71
	v_cvt_pk_bf16_f32 v70, v64, v65
	v_add_u32_e32 v64, 0x1080, v131
	v_ashrrev_i32_e32 v65, 31, v64
	v_lshlrev_b64 v[64:65], 12, v[64:65]
	v_lshl_add_u64 v[64:65], s[4:5], 0, v[64:65]
	v_lshl_add_u64 v[64:65], v[64:65], 0, v[178:179]
	v_cvt_pk_bf16_f32 v71, v66, v67
	global_store_dwordx4 v[80:81], v[68:71], off offset:256
	v_cvt_pk_bf16_f32 v60, v60, v61
	v_cvt_pk_bf16_f32 v61, v62, v63
	v_cvt_pk_bf16_f32 v62, v56, v57
	v_cvt_pk_bf16_f32 v63, v58, v59
	global_store_dwordx4 v[64:65], v[60:63], off
	v_cvt_pk_bf16_f32 v48, v48, v49
	v_cvt_pk_bf16_f32 v49, v50, v51
	v_cvt_pk_bf16_f32 v50, v40, v41
	v_add_u32_e32 v40, 0x1090, v131
	v_ashrrev_i32_e32 v41, 31, v40
	v_lshlrev_b64 v[40:41], 12, v[40:41]
	v_lshl_add_u64 v[40:41], s[4:5], 0, v[40:41]
	v_cvt_pk_bf16_f32 v51, v42, v43
	global_store_dwordx4 v[64:65], v[48:51], off offset:256
	s_nop 1
	v_lshl_add_u64 v[48:49], v[40:41], 0, v[178:179]
	v_cvt_pk_bf16_f32 v40, v52, v53
	v_cvt_pk_bf16_f32 v41, v54, v55
	v_cvt_pk_bf16_f32 v42, v44, v45
	v_cvt_pk_bf16_f32 v43, v46, v47
	global_store_dwordx4 v[48:49], v[40:43], off
	v_cvt_pk_bf16_f32 v32, v32, v33
	v_cvt_pk_bf16_f32 v33, v34, v35
	v_cvt_pk_bf16_f32 v34, v24, v25
	v_add_u32_e32 v24, 0x10a0, v131
	v_ashrrev_i32_e32 v25, 31, v24
	v_lshlrev_b64 v[24:25], 12, v[24:25]
	v_lshl_add_u64 v[24:25], s[4:5], 0, v[24:25]
	v_cvt_pk_bf16_f32 v35, v26, v27
	global_store_dwordx4 v[48:49], v[32:35], off offset:256
	s_nop 1
	v_lshl_add_u64 v[32:33], v[24:25], 0, v[178:179]
	v_cvt_pk_bf16_f32 v24, v36, v37
	v_cvt_pk_bf16_f32 v25, v38, v39
	v_cvt_pk_bf16_f32 v26, v28, v29
	v_cvt_pk_bf16_f32 v27, v30, v31
	global_store_dwordx4 v[32:33], v[24:27], off
	v_cvt_pk_bf16_f32 v16, v16, v17
	v_cvt_pk_bf16_f32 v17, v18, v19
	v_cvt_pk_bf16_f32 v18, v8, v9
	v_add_u32_e32 v8, 0x10b0, v131
	v_ashrrev_i32_e32 v9, 31, v8
	v_lshlrev_b64 v[8:9], 12, v[8:9]
	v_lshl_add_u64 v[8:9], s[4:5], 0, v[8:9]
	v_cvt_pk_bf16_f32 v19, v10, v11
	global_store_dwordx4 v[32:33], v[16:19], off offset:256
	s_nop 1
	v_lshl_add_u64 v[16:17], v[8:9], 0, v[178:179]
	v_cvt_pk_bf16_f32 v8, v20, v21
	v_cvt_pk_bf16_f32 v9, v22, v23
	v_cvt_pk_bf16_f32 v10, v12, v13
	v_cvt_pk_bf16_f32 v11, v14, v15
	global_store_dwordx4 v[16:17], v[8:11], off
	v_cvt_pk_bf16_f32 v4, v4, v5
	v_cvt_pk_bf16_f32 v5, v6, v7
	v_cvt_pk_bf16_f32 v6, v0, v1
	v_cvt_pk_bf16_f32 v7, v2, v3
	global_store_dwordx4 v[16:17], v[4:7], off offset:256
	s_waitcnt vmcnt(0)
	s_cmp_lt_u32 s6, 4
	s_cbranch_scc0 .LBB0_938
	s_barrier

.LBB0_943:
	s_add_u32 s12, s10, 0xf3ce0080
	s_addc_u32 s13, s11, -1
	s_cmp_lg_u32 s20, 4
	s_cselect_b32 s12, s12, 0
	s_cselect_b32 s13, s13, 0
	s_add_u32 s14, s6, s12
	s_addc_u32 s15, s7, s13
	s_add_i32 s21, 0, 0x10000
	v_add_u32_e32 v150, s21, v140
	ds_read_b128 v[142:145], v150
	ds_read_b128 v[146:149], v150 offset:1024
	ds_read_b128 v[154:157], v150 offset:2048
	ds_read_b128 v[158:161], v150 offset:3072
	s_add_u32 s12, s8, s12
	s_addc_u32 s13, s9, s13
	v_lshl_add_u64 v[150:151], v[136:137], 0, s[10:11]
	s_add_i32 m0, s22, 0xc000
	ds_read_b128 v[162:165], v141
	ds_read_b128 v[166:169], v141 offset:1024
	ds_read_b128 v[170:173], v141 offset:2048
	ds_read_b128 v[174:177], v141 offset:3072
	ds_read_b128 v[180:183], v141 offset:4096
	ds_read_b128 v[184:187], v141 offset:5120
	ds_read_b128 v[188:191], v141 offset:6144
	ds_read_b128 v[192:195], v141 offset:7168
	global_load_lds_dwordx4 v[150:151], off
	v_lshl_add_u64 v[150:151], v[134:135], 0, s[10:11]
	s_add_i32 m0, s22, 0xe000
	s_nop 0
	global_load_lds_dwordx4 v[150:151], off
	s_waitcnt lgkmcnt(8)
	s_barrier
	s_waitcnt lgkmcnt(0)
	s_waitcnt lgkmcnt(0)
	v_mfma_f32_16x16x32_bf16 v[124:127], v[142:145], v[162:165], v[124:127]
	v_mfma_f32_16x16x32_bf16 v[120:123], v[154:157], v[162:165], v[120:123]
	v_mfma_f32_16x16x32_bf16 v[116:119], v[142:145], v[170:173], v[116:119]
	v_mfma_f32_16x16x32_bf16 v[108:111], v[154:157], v[170:173], v[108:111]
	v_mfma_f32_16x16x32_bf16 v[100:103], v[142:145], v[180:183], v[100:103]
	v_mfma_f32_16x16x32_bf16 v[92:95], v[154:157], v[180:183], v[92:95]
	v_mfma_f32_16x16x32_bf16 v[84:87], v[142:145], v[188:191], v[84:87]
	v_mfma_f32_16x16x32_bf16 v[76:79], v[154:157], v[188:191], v[76:79]
	v_mfma_f32_16x16x32_bf16 v[124:127], v[146:149], v[166:169], v[124:127]
	v_mfma_f32_16x16x32_bf16 v[120:123], v[158:161], v[166:169], v[120:123]
	v_mfma_f32_16x16x32_bf16 v[116:119], v[146:149], v[174:177], v[116:119]
	v_mfma_f32_16x16x32_bf16 v[108:111], v[158:161], v[174:177], v[108:111]
	v_mfma_f32_16x16x32_bf16 v[100:103], v[146:149], v[184:187], v[100:103]
	v_mfma_f32_16x16x32_bf16 v[92:95], v[158:161], v[184:187], v[92:95]
	v_mfma_f32_16x16x32_bf16 v[84:87], v[146:149], v[192:195], v[84:87]
	v_mfma_f32_16x16x32_bf16 v[76:79], v[158:161], v[192:195], v[76:79]
	s_barrier
	s_add_i32 s28, 0, 0x14000
	v_add_u32_e32 v150, s28, v140
	s_add_i32 s21, s21, s16
	ds_read_b128 v[196:199], v150
	ds_read_b128 v[224:227], v150 offset:1024
	ds_read_b128 v[228:231], v150 offset:2048
	ds_read_b128 v[232:235], v150 offset:3072
	s_mov_b32 m0, s21
	global_load_lds_dwordx4 v178, s[12:13]
	s_add_i32 m0, s21, 0x2000
	s_nop 0
	global_load_lds_dwordx4 v128, s[12:13]
	s_barrier
	s_waitcnt lgkmcnt(0)
	s_waitcnt lgkmcnt(0)
	v_mfma_f32_16x16x32_bf16 v[112:115], v[196:199], v[162:165], v[112:115]
	v_mfma_f32_16x16x32_bf16 v[104:107], v[228:231], v[162:165], v[104:107]
	v_mfma_f32_16x16x32_bf16 v[96:99], v[196:199], v[170:173], v[96:99]
	v_mfma_f32_16x16x32_bf16 v[88:91], v[228:231], v[170:173], v[88:91]
	v_mfma_f32_16x16x32_bf16 v[80:83], v[196:199], v[180:183], v[80:83]
	v_mfma_f32_16x16x32_bf16 v[72:75], v[228:231], v[180:183], v[72:75]
	v_mfma_f32_16x16x32_bf16 v[68:71], v[196:199], v[188:191], v[68:71]
	v_mfma_f32_16x16x32_bf16 v[64:67], v[228:231], v[188:191], v[64:67]
	v_mfma_f32_16x16x32_bf16 v[112:115], v[224:227], v[166:169], v[112:115]
	v_mfma_f32_16x16x32_bf16 v[104:107], v[232:235], v[166:169], v[104:107]
	v_mfma_f32_16x16x32_bf16 v[96:99], v[224:227], v[174:177], v[96:99]
	v_mfma_f32_16x16x32_bf16 v[88:91], v[232:235], v[174:177], v[88:91]
	v_mfma_f32_16x16x32_bf16 v[80:83], v[224:227], v[184:187], v[80:83]
	v_mfma_f32_16x16x32_bf16 v[72:75], v[232:235], v[184:187], v[72:75]
	v_mfma_f32_16x16x32_bf16 v[68:71], v[224:227], v[192:195], v[68:71]
	v_mfma_f32_16x16x32_bf16 v[64:67], v[232:235], v[192:195], v[64:67]
	s_mov_b32 m0, s22
	s_mov_b64 s[100:101], s[14:15]
	s_barrier
	ds_read_b128 v[162:165], v141 offset:16384
	ds_read_b128 v[166:169], v141 offset:17408
	ds_read_b128 v[170:173], v141 offset:18432
	ds_read_b128 v[174:177], v141 offset:19456
	ds_read_b128 v[180:183], v141 offset:20480
	ds_read_b128 v[184:187], v141 offset:21504
	ds_read_b128 v[188:191], v141 offset:22528
	ds_read_b128 v[192:195], v141 offset:23552
	global_load_lds_dwordx4 v132, s[14:15]
	s_mov_b64 s[100:101], s[14:15]
	s_mov_b32 m0, s23
	s_nop 0
	global_load_lds_dwordx4 v130, s[14:15]
	s_barrier
	s_waitcnt lgkmcnt(0)
	s_waitcnt lgkmcnt(0)
	v_mfma_f32_16x16x32_bf16 v[60:63], v[142:145], v[162:165], v[60:63]
	v_mfma_f32_16x16x32_bf16 v[56:59], v[154:157], v[162:165], v[56:59]
	v_mfma_f32_16x16x32_bf16 v[52:55], v[142:145], v[170:173], v[52:55]
	v_mfma_f32_16x16x32_bf16 v[44:47], v[154:157], v[170:173], v[44:47]
	v_mfma_f32_16x16x32_bf16 v[36:39], v[142:145], v[180:183], v[36:39]
	v_mfma_f32_16x16x32_bf16 v[28:31], v[154:157], v[180:183], v[28:31]
	v_mfma_f32_16x16x32_bf16 v[20:23], v[142:145], v[188:191], v[20:23]
	v_mfma_f32_16x16x32_bf16 v[12:15], v[154:157], v[188:191], v[12:15]
	v_mfma_f32_16x16x32_bf16 v[60:63], v[146:149], v[166:169], v[60:63]
	v_mfma_f32_16x16x32_bf16 v[56:59], v[158:161], v[166:169], v[56:59]
	v_mfma_f32_16x16x32_bf16 v[52:55], v[146:149], v[174:177], v[52:55]
	v_mfma_f32_16x16x32_bf16 v[44:47], v[158:161], v[174:177], v[44:47]
	v_mfma_f32_16x16x32_bf16 v[36:39], v[146:149], v[184:187], v[36:39]
	v_mfma_f32_16x16x32_bf16 v[28:31], v[158:161], v[184:187], v[28:31]
	v_mfma_f32_16x16x32_bf16 v[20:23], v[146:149], v[192:195], v[20:23]
	v_mfma_f32_16x16x32_bf16 v[12:15], v[158:161], v[192:195], v[12:15]
	s_barrier
	s_add_u32 s26, s12, 0x20000
	s_addc_u32 s27, s13, 0
	s_add_i32 s21, s28, s16
	s_mov_b32 m0, s21
	s_nop 0
	global_load_lds_dwordx4 v178, s[26:27]
	s_add_i32 m0, s21, 0x2000
	s_nop 0
	global_load_lds_dwordx4 v128, s[26:27]
	s_waitcnt vmcnt(6)
	s_barrier
	v_mfma_f32_16x16x32_bf16 v[48:51], v[196:199], v[162:165], v[48:51]
	v_mfma_f32_16x16x32_bf16 v[40:43], v[228:231], v[162:165], v[40:43]
	v_mfma_f32_16x16x32_bf16 v[32:35], v[196:199], v[170:173], v[32:35]
	v_mfma_f32_16x16x32_bf16 v[24:27], v[228:231], v[170:173], v[24:27]
	v_mfma_f32_16x16x32_bf16 v[16:19], v[196:199], v[180:183], v[16:19]
	v_mfma_f32_16x16x32_bf16 v[8:11], v[228:231], v[180:183], v[8:11]
	v_mfma_f32_16x16x32_bf16 v[4:7], v[196:199], v[188:191], v[4:7]
	v_mfma_f32_16x16x32_bf16 v[0:3], v[228:231], v[188:191], v[0:3]
	v_mfma_f32_16x16x32_bf16 v[48:51], v[224:227], v[166:169], v[48:51]
	v_mfma_f32_16x16x32_bf16 v[40:43], v[232:235], v[166:169], v[40:43]
	v_mfma_f32_16x16x32_bf16 v[32:35], v[224:227], v[174:177], v[32:35]
	v_mfma_f32_16x16x32_bf16 v[24:27], v[232:235], v[174:177], v[24:27]
	v_mfma_f32_16x16x32_bf16 v[16:19], v[224:227], v[184:187], v[16:19]
	v_mfma_f32_16x16x32_bf16 v[8:11], v[232:235], v[184:187], v[8:11]
	v_mfma_f32_16x16x32_bf16 v[4:7], v[224:227], v[192:195], v[4:7]
	v_mfma_f32_16x16x32_bf16 v[0:3], v[232:235], v[192:195], v[0:3]
	s_add_i32 s21, 0, 0x18000
	v_add_u32_e32 v153, s21, v140
	s_barrier
	ds_read_b128 v[142:145], v153
	ds_read_b128 v[146:149], v153 offset:1024
	ds_read_b128 v[154:157], v153 offset:2048
	ds_read_b128 v[158:161], v153 offset:3072
	s_add_u32 s14, s14, 0x20000
	s_addc_u32 s15, s15, 0
	s_mov_b32 m0, s24
	ds_read_b128 v[162:165], v141 offset:32768
	ds_read_b128 v[166:169], v141 offset:33792
	ds_read_b128 v[170:173], v141 offset:34816
	ds_read_b128 v[174:177], v141 offset:35840
	ds_read_b128 v[180:183], v141 offset:36864
	ds_read_b128 v[184:187], v141 offset:37888
	ds_read_b128 v[188:191], v141 offset:38912
	ds_read_b128 v[192:195], v141 offset:39936
	global_load_lds_dwordx4 v132, s[14:15]
	s_mov_b32 m0, s25
	s_nop 0
	global_load_lds_dwordx4 v130, s[14:15]
	s_waitcnt lgkmcnt(8)
	s_barrier
	s_waitcnt lgkmcnt(0)
	s_waitcnt lgkmcnt(0)
	v_mfma_f32_16x16x32_bf16 v[124:127], v[142:145], v[162:165], v[124:127]
	v_mfma_f32_16x16x32_bf16 v[120:123], v[154:157], v[162:165], v[120:123]
	v_mfma_f32_16x16x32_bf16 v[116:119], v[142:145], v[170:173], v[116:119]
	v_mfma_f32_16x16x32_bf16 v[108:111], v[154:157], v[170:173], v[108:111]
	v_mfma_f32_16x16x32_bf16 v[100:103], v[142:145], v[180:183], v[100:103]
	v_mfma_f32_16x16x32_bf16 v[92:95], v[154:157], v[180:183], v[92:95]
	v_mfma_f32_16x16x32_bf16 v[84:87], v[142:145], v[188:191], v[84:87]
	v_mfma_f32_16x16x32_bf16 v[76:79], v[154:157], v[188:191], v[76:79]
	v_mfma_f32_16x16x32_bf16 v[124:127], v[146:149], v[166:169], v[124:127]
	v_mfma_f32_16x16x32_bf16 v[120:123], v[158:161], v[166:169], v[120:123]
	v_mfma_f32_16x16x32_bf16 v[116:119], v[146:149], v[174:177], v[116:119]
	v_mfma_f32_16x16x32_bf16 v[108:111], v[158:161], v[174:177], v[108:111]
	v_mfma_f32_16x16x32_bf16 v[100:103], v[146:149], v[184:187], v[100:103]
	v_mfma_f32_16x16x32_bf16 v[92:95], v[158:161], v[184:187], v[92:95]
	v_mfma_f32_16x16x32_bf16 v[84:87], v[146:149], v[192:195], v[84:87]
	v_mfma_f32_16x16x32_bf16 v[76:79], v[158:161], v[192:195], v[76:79]
	s_barrier
	s_add_i32 s14, 0, 0x1c000
	s_add_i32 s15, s21, s16
	v_add_u32_e32 v153, s14, v140
	s_add_i32 m0, s15, 0xffffff80
	ds_read_b128 v[196:199], v153
	ds_read_b128 v[224:227], v153 offset:1024
	ds_read_b128 v[228:231], v153 offset:2048
	ds_read_b128 v[232:235], v153 offset:3072
	global_load_lds_dwordx4 v178, s[12:13] offset:128
	s_add_i32 m0, s15, 0x1f80
	s_nop 0
	global_load_lds_dwordx4 v128, s[12:13] offset:128
	s_barrier
	s_waitcnt lgkmcnt(0)
	s_waitcnt lgkmcnt(0)
	v_mfma_f32_16x16x32_bf16 v[112:115], v[196:199], v[162:165], v[112:115]
	v_mfma_f32_16x16x32_bf16 v[104:107], v[228:231], v[162:165], v[104:107]
	v_mfma_f32_16x16x32_bf16 v[96:99], v[196:199], v[170:173], v[96:99]
	v_mfma_f32_16x16x32_bf16 v[88:91], v[228:231], v[170:173], v[88:91]
	v_mfma_f32_16x16x32_bf16 v[80:83], v[196:199], v[180:183], v[80:83]
	v_mfma_f32_16x16x32_bf16 v[72:75], v[228:231], v[180:183], v[72:75]
	v_mfma_f32_16x16x32_bf16 v[68:71], v[196:199], v[188:191], v[68:71]
	v_mfma_f32_16x16x32_bf16 v[64:67], v[228:231], v[188:191], v[64:67]
	v_mfma_f32_16x16x32_bf16 v[112:115], v[224:227], v[166:169], v[112:115]
	v_mfma_f32_16x16x32_bf16 v[104:107], v[232:235], v[166:169], v[104:107]
	v_mfma_f32_16x16x32_bf16 v[96:99], v[224:227], v[174:177], v[96:99]
	v_mfma_f32_16x16x32_bf16 v[88:91], v[232:235], v[174:177], v[88:91]
	v_mfma_f32_16x16x32_bf16 v[80:83], v[224:227], v[184:187], v[80:83]
	v_mfma_f32_16x16x32_bf16 v[72:75], v[232:235], v[184:187], v[72:75]
	v_mfma_f32_16x16x32_bf16 v[68:71], v[224:227], v[192:195], v[68:71]
	v_mfma_f32_16x16x32_bf16 v[64:67], v[232:235], v[192:195], v[64:67]
	s_add_i32 m0, s18, 0xffffff80
	s_barrier
	ds_read_b128 v[162:165], v141 offset:49152
	ds_read_b128 v[166:169], v141 offset:50176
	ds_read_b128 v[170:173], v141 offset:51200
	ds_read_b128 v[174:177], v141 offset:52224
	ds_read_b128 v[180:183], v141 offset:53248
	ds_read_b128 v[184:187], v141 offset:54272
	ds_read_b128 v[188:191], v141 offset:55296
	ds_read_b128 v[192:195], v141 offset:56320
	global_load_lds_dwordx4 v132, s[100:101] offset:128
	s_add_i32 m0, s19, 0xffffff80
	s_nop 0
	global_load_lds_dwordx4 v130, s[100:101] offset:128
	s_barrier
	s_waitcnt lgkmcnt(0)
	s_waitcnt lgkmcnt(0)
	v_mfma_f32_16x16x32_bf16 v[60:63], v[142:145], v[162:165], v[60:63]
	v_mfma_f32_16x16x32_bf16 v[56:59], v[154:157], v[162:165], v[56:59]
	v_mfma_f32_16x16x32_bf16 v[52:55], v[142:145], v[170:173], v[52:55]
	v_mfma_f32_16x16x32_bf16 v[44:47], v[154:157], v[170:173], v[44:47]
	v_mfma_f32_16x16x32_bf16 v[36:39], v[142:145], v[180:183], v[36:39]
	v_mfma_f32_16x16x32_bf16 v[28:31], v[154:157], v[180:183], v[28:31]
	v_mfma_f32_16x16x32_bf16 v[20:23], v[142:145], v[188:191], v[20:23]
	v_mfma_f32_16x16x32_bf16 v[12:15], v[154:157], v[188:191], v[12:15]
	v_mfma_f32_16x16x32_bf16 v[60:63], v[146:149], v[166:169], v[60:63]
	v_mfma_f32_16x16x32_bf16 v[56:59], v[158:161], v[166:169], v[56:59]
	v_mfma_f32_16x16x32_bf16 v[52:55], v[146:149], v[174:177], v[52:55]
	v_mfma_f32_16x16x32_bf16 v[44:47], v[158:161], v[174:177], v[44:47]
	v_mfma_f32_16x16x32_bf16 v[36:39], v[146:149], v[184:187], v[36:39]
	v_mfma_f32_16x16x32_bf16 v[28:31], v[158:161], v[184:187], v[28:31]
	v_mfma_f32_16x16x32_bf16 v[20:23], v[146:149], v[192:195], v[20:23]
	v_mfma_f32_16x16x32_bf16 v[12:15], v[158:161], v[192:195], v[12:15]
	s_barrier
	s_add_u32 s12, s12, 0x20080
	s_addc_u32 s13, s13, 0
	s_add_i32 s14, s14, s16
	s_mov_b32 m0, s14
	s_nop 0
	global_load_lds_dwordx4 v178, s[12:13]
	s_add_i32 m0, s14, 0x2000
	s_nop 0
	global_load_lds_dwordx4 v128, s[12:13]
	s_waitcnt vmcnt(6)
	s_barrier
	v_mfma_f32_16x16x32_bf16 v[48:51], v[196:199], v[162:165], v[48:51]
	v_mfma_f32_16x16x32_bf16 v[40:43], v[228:231], v[162:165], v[40:43]
	v_mfma_f32_16x16x32_bf16 v[32:35], v[196:199], v[170:173], v[32:35]
	v_mfma_f32_16x16x32_bf16 v[24:27], v[228:231], v[170:173], v[24:27]
	v_mfma_f32_16x16x32_bf16 v[16:19], v[196:199], v[180:183], v[16:19]
	v_mfma_f32_16x16x32_bf16 v[8:11], v[228:231], v[180:183], v[8:11]
	v_mfma_f32_16x16x32_bf16 v[4:7], v[196:199], v[188:191], v[4:7]
	v_mfma_f32_16x16x32_bf16 v[0:3], v[228:231], v[188:191], v[0:3]
	v_mfma_f32_16x16x32_bf16 v[48:51], v[224:227], v[166:169], v[48:51]
	v_mfma_f32_16x16x32_bf16 v[40:43], v[232:235], v[166:169], v[40:43]
	v_mfma_f32_16x16x32_bf16 v[32:35], v[224:227], v[174:177], v[32:35]
	v_mfma_f32_16x16x32_bf16 v[24:27], v[232:235], v[174:177], v[24:27]
	v_mfma_f32_16x16x32_bf16 v[16:19], v[224:227], v[184:187], v[16:19]
	v_mfma_f32_16x16x32_bf16 v[8:11], v[232:235], v[184:187], v[8:11]
	v_mfma_f32_16x16x32_bf16 v[4:7], v[224:227], v[192:195], v[4:7]
	v_mfma_f32_16x16x32_bf16 v[0:3], v[232:235], v[192:195], v[0:3]
	s_add_i32 s20, s20, 2
	s_add_u32 s10, s10, 0x100
	s_addc_u32 s11, s11, 0
	s_cmp_gt_u32 s20, 5
	s_barrier
	s_cbranch_scc0 .LBB0_943
	v_readlane_b32 s6, v254, 23
	s_or_b32 s6, s17, s6
	v_cvt_pk_bf16_f32 v124, v124, v125
	v_cvt_pk_bf16_f32 v125, v126, v127
	v_cvt_pk_bf16_f32 v126, v120, v121
	v_cvt_pk_bf16_f32 v127, v122, v123
	s_nop 0
	v_or_b32_e32 v132, s6, v139
	v_readlane_b32 s6, v254, 25
	v_lshlrev_b32_e32 v178, 1, v132
	s_nop 0
	v_add_u32_e32 v128, s6, v138
	v_ashrrev_i32_e32 v129, 31, v128
	v_lshlrev_b64 v[130:131], 12, v[128:129]
	v_lshl_add_u64 v[130:131], s[4:5], 0, v[130:131]
	v_lshl_add_u64 v[130:131], v[130:131], 0, v[178:179]
	global_store_dwordx4 v[130:131], v[124:127], off
	v_cvt_pk_bf16_f32 v112, v112, v113
	v_cvt_pk_bf16_f32 v113, v114, v115
	v_cvt_pk_bf16_f32 v114, v104, v105
	v_or_b32_e32 v104, 16, v128
	v_ashrrev_i32_e32 v105, 31, v104
	v_lshlrev_b64 v[104:105], 12, v[104:105]
	v_lshl_add_u64 v[104:105], s[4:5], 0, v[104:105]
	v_cvt_pk_bf16_f32 v115, v106, v107
	global_store_dwordx4 v[130:131], v[112:115], off offset:256
	s_nop 1
	v_lshl_add_u64 v[112:113], v[104:105], 0, v[178:179]
	v_cvt_pk_bf16_f32 v104, v116, v117
	v_cvt_pk_bf16_f32 v105, v118, v119
	v_cvt_pk_bf16_f32 v106, v108, v109
	v_cvt_pk_bf16_f32 v107, v110, v111
	global_store_dwordx4 v[112:113], v[104:107], off
	v_cvt_pk_bf16_f32 v96, v96, v97
	v_cvt_pk_bf16_f32 v97, v98, v99
	v_cvt_pk_bf16_f32 v98, v88, v89
	v_or_b32_e32 v88, 32, v128
	v_ashrrev_i32_e32 v89, 31, v88
	v_lshlrev_b64 v[88:89], 12, v[88:89]
	v_lshl_add_u64 v[88:89], s[4:5], 0, v[88:89]
	v_cvt_pk_bf16_f32 v99, v90, v91
	global_store_dwordx4 v[112:113], v[96:99], off offset:256
	s_nop 1
	v_lshl_add_u64 v[96:97], v[88:89], 0, v[178:179]
	v_cvt_pk_bf16_f32 v88, v100, v101
	v_cvt_pk_bf16_f32 v89, v102, v103
	v_cvt_pk_bf16_f32 v90, v92, v93
	v_cvt_pk_bf16_f32 v91, v94, v95
	global_store_dwordx4 v[96:97], v[88:91], off
	v_cvt_pk_bf16_f32 v80, v80, v81
	v_cvt_pk_bf16_f32 v81, v82, v83
	v_cvt_pk_bf16_f32 v82, v72, v73
	v_or_b32_e32 v72, 48, v128
	v_ashrrev_i32_e32 v73, 31, v72
	v_lshlrev_b64 v[72:73], 12, v[72:73]
	v_lshl_add_u64 v[72:73], s[4:5], 0, v[72:73]
	v_cvt_pk_bf16_f32 v83, v74, v75
	global_store_dwordx4 v[96:97], v[80:83], off offset:256
	s_nop 1
	v_lshl_add_u64 v[80:81], v[72:73], 0, v[178:179]
	v_cvt_pk_bf16_f32 v72, v84, v85
	v_cvt_pk_bf16_f32 v73, v86, v87
	v_cvt_pk_bf16_f32 v74, v76, v77
	v_cvt_pk_bf16_f32 v75, v78, v79
	global_store_dwordx4 v[80:81], v[72:75], off
	v_cvt_pk_bf16_f32 v68, v68, v69
	v_cvt_pk_bf16_f32 v69, v70, v71
	v_cvt_pk_bf16_f32 v70, v64, v65
	v_add_u32_e32 v64, 0x80, v128
	v_ashrrev_i32_e32 v65, 31, v64
	v_lshlrev_b64 v[64:65], 12, v[64:65]
	v_lshl_add_u64 v[64:65], s[4:5], 0, v[64:65]
	v_lshl_add_u64 v[64:65], v[64:65], 0, v[178:179]
	v_cvt_pk_bf16_f32 v71, v66, v67
	global_store_dwordx4 v[80:81], v[68:71], off offset:256
	v_cvt_pk_bf16_f32 v60, v60, v61
	v_cvt_pk_bf16_f32 v61, v62, v63
	v_cvt_pk_bf16_f32 v62, v56, v57
	v_cvt_pk_bf16_f32 v63, v58, v59
	global_store_dwordx4 v[64:65], v[60:63], off
	v_cvt_pk_bf16_f32 v48, v48, v49
	v_cvt_pk_bf16_f32 v49, v50, v51
	v_cvt_pk_bf16_f32 v50, v40, v41
	v_add_u32_e32 v40, 0x90, v128
	v_ashrrev_i32_e32 v41, 31, v40
	v_lshlrev_b64 v[40:41], 12, v[40:41]
	v_lshl_add_u64 v[40:41], s[4:5], 0, v[40:41]
	v_cvt_pk_bf16_f32 v51, v42, v43
	global_store_dwordx4 v[64:65], v[48:51], off offset:256
	s_nop 1
	v_lshl_add_u64 v[48:49], v[40:41], 0, v[178:179]
	v_cvt_pk_bf16_f32 v40, v52, v53
	v_cvt_pk_bf16_f32 v41, v54, v55
	v_cvt_pk_bf16_f32 v42, v44, v45
	v_cvt_pk_bf16_f32 v43, v46, v47
	global_store_dwordx4 v[48:49], v[40:43], off
	v_cvt_pk_bf16_f32 v32, v32, v33
	v_cvt_pk_bf16_f32 v33, v34, v35
	v_cvt_pk_bf16_f32 v34, v24, v25
	v_add_u32_e32 v24, 0xa0, v128
	v_ashrrev_i32_e32 v25, 31, v24
	v_lshlrev_b64 v[24:25], 12, v[24:25]
	v_lshl_add_u64 v[24:25], s[4:5], 0, v[24:25]
	v_cvt_pk_bf16_f32 v35, v26, v27
	global_store_dwordx4 v[48:49], v[32:35], off offset:256
	s_nop 1
	v_lshl_add_u64 v[32:33], v[24:25], 0, v[178:179]
	v_cvt_pk_bf16_f32 v24, v36, v37
	v_cvt_pk_bf16_f32 v25, v38, v39
	v_cvt_pk_bf16_f32 v26, v28, v29
	v_cvt_pk_bf16_f32 v27, v30, v31
	global_store_dwordx4 v[32:33], v[24:27], off
	v_cvt_pk_bf16_f32 v16, v16, v17
	v_cvt_pk_bf16_f32 v17, v18, v19
	v_cvt_pk_bf16_f32 v18, v8, v9
	v_add_u32_e32 v8, 0xb0, v128
	v_ashrrev_i32_e32 v9, 31, v8
	v_lshlrev_b64 v[8:9], 12, v[8:9]
	v_lshl_add_u64 v[8:9], s[4:5], 0, v[8:9]
	v_cvt_pk_bf16_f32 v19, v10, v11
	global_store_dwordx4 v[32:33], v[16:19], off offset:256
	v_readlane_b32 s4, v255, 8
	s_nop 0
	v_lshl_add_u64 v[16:17], v[8:9], 0, v[178:179]
	v_cvt_pk_bf16_f32 v8, v20, v21
	v_cvt_pk_bf16_f32 v9, v22, v23
	v_cvt_pk_bf16_f32 v10, v12, v13
	v_cvt_pk_bf16_f32 v11, v14, v15
	global_store_dwordx4 v[16:17], v[8:11], off
	v_cvt_pk_bf16_f32 v4, v4, v5
	v_cvt_pk_bf16_f32 v5, v6, v7
	v_cvt_pk_bf16_f32 v6, v0, v1
	v_cvt_pk_bf16_f32 v7, v2, v3
	global_store_dwordx4 v[16:17], v[4:7], off offset:256
	s_waitcnt vmcnt(0)
	s_cmp_lt_u32 s4, 4
	s_cbranch_scc0 .LBB0_946
	s_barrier

.LBB0_1077:
	s_add_u32 s18, s16, 0x100
	s_addc_u32 s19, s17, 0
	s_add_i32 s66, 0, 0x10000
	v_add_u32_e32 v140, s66, v157
	ds_read_b128 v[128:131], v140
	ds_read_b128 v[132:135], v140 offset:1024
	ds_read_b128 v[136:139], v140 offset:2048
	ds_read_b128 v[140:143], v140 offset:3072
	s_cmp_eq_u32 s63, 28
	s_cselect_b32 s23, s13, s19
	s_cselect_b32 s22, s12, s18
	s_cselect_b32 s21, s15, s62
	s_cselect_b32 s20, s14, s5
	v_lshl_add_u64 v[154:155], s[16:17], 0, v[148:149]
	s_add_i32 m0, s29, 0xc000
	ds_read_b128 v[150:153], v159
	ds_read_b128 v[160:163], v159 offset:1024
	ds_read_b128 v[164:167], v159 offset:2048
	ds_read_b128 v[168:171], v159 offset:3072
	ds_read_b128 v[172:175], v159 offset:4096
	ds_read_b128 v[180:183], v159 offset:5120
	ds_read_b128 v[184:187], v159 offset:6144
	ds_read_b128 v[188:191], v159 offset:7168
	global_load_lds_dwordx4 v[154:155], off
	v_lshl_add_u64 v[154:155], s[16:17], 0, v[146:147]
	s_add_i32 m0, s29, 0xe000
	s_nop 0
	global_load_lds_dwordx4 v[154:155], off
	s_waitcnt lgkmcnt(8)
	s_barrier
	s_waitcnt lgkmcnt(0)
	s_waitcnt lgkmcnt(0)
	v_mfma_f32_16x16x32_bf16 v[124:127], v[128:131], v[150:153], v[124:127]
	v_mfma_f32_16x16x32_bf16 v[120:123], v[136:139], v[150:153], v[120:123]
	v_mfma_f32_16x16x32_bf16 v[108:111], v[128:131], v[164:167], v[108:111]
	v_mfma_f32_16x16x32_bf16 v[104:107], v[136:139], v[164:167], v[104:107]
	v_mfma_f32_16x16x32_bf16 v[92:95], v[128:131], v[172:175], v[92:95]
	v_mfma_f32_16x16x32_bf16 v[88:91], v[136:139], v[172:175], v[88:91]
	v_mfma_f32_16x16x32_bf16 v[76:79], v[128:131], v[184:187], v[76:79]
	v_mfma_f32_16x16x32_bf16 v[72:75], v[136:139], v[184:187], v[72:75]
	v_mfma_f32_16x16x32_bf16 v[124:127], v[132:135], v[160:163], v[124:127]
	v_mfma_f32_16x16x32_bf16 v[120:123], v[140:143], v[160:163], v[120:123]
	v_mfma_f32_16x16x32_bf16 v[108:111], v[132:135], v[168:171], v[108:111]
	v_mfma_f32_16x16x32_bf16 v[104:107], v[140:143], v[168:171], v[104:107]
	v_mfma_f32_16x16x32_bf16 v[92:95], v[132:135], v[180:183], v[92:95]
	v_mfma_f32_16x16x32_bf16 v[88:91], v[140:143], v[180:183], v[88:91]
	v_mfma_f32_16x16x32_bf16 v[76:79], v[132:135], v[188:191], v[76:79]
	v_mfma_f32_16x16x32_bf16 v[72:75], v[140:143], v[188:191], v[72:75]
	s_barrier
	s_add_i32 s67, 0, 0x14000
	v_add_u32_e32 v154, s67, v157
	s_add_i32 s16, s66, s28
	ds_read_b128 v[192:195], v154
	ds_read_b128 v[196:199], v154 offset:1024
	ds_read_b128 v[204:207], v154 offset:2048
	ds_read_b128 v[212:215], v154 offset:3072
	s_mov_b32 m0, s16
	global_load_lds_dwordx4 v178, s[20:21]
	s_add_i32 m0, s16, 0x2000
	s_nop 0
	global_load_lds_dwordx4 v144, s[20:21]
	s_barrier
	s_waitcnt lgkmcnt(0)
	s_waitcnt lgkmcnt(0)
	v_mfma_f32_16x16x32_bf16 v[116:119], v[192:195], v[150:153], v[116:119]
	v_mfma_f32_16x16x32_bf16 v[112:115], v[204:207], v[150:153], v[112:115]
	v_mfma_f32_16x16x32_bf16 v[100:103], v[192:195], v[164:167], v[100:103]
	v_mfma_f32_16x16x32_bf16 v[96:99], v[204:207], v[164:167], v[96:99]
	v_mfma_f32_16x16x32_bf16 v[84:87], v[192:195], v[172:175], v[84:87]
	v_mfma_f32_16x16x32_bf16 v[80:83], v[204:207], v[172:175], v[80:83]
	v_mfma_f32_16x16x32_bf16 v[68:71], v[192:195], v[184:187], v[68:71]
	v_mfma_f32_16x16x32_bf16 v[64:67], v[204:207], v[184:187], v[64:67]
	v_mfma_f32_16x16x32_bf16 v[116:119], v[196:199], v[160:163], v[116:119]
	v_mfma_f32_16x16x32_bf16 v[112:115], v[212:215], v[160:163], v[112:115]
	v_mfma_f32_16x16x32_bf16 v[100:103], v[196:199], v[168:171], v[100:103]
	v_mfma_f32_16x16x32_bf16 v[96:99], v[212:215], v[168:171], v[96:99]
	v_mfma_f32_16x16x32_bf16 v[84:87], v[196:199], v[180:183], v[84:87]
	v_mfma_f32_16x16x32_bf16 v[80:83], v[212:215], v[180:183], v[80:83]
	v_mfma_f32_16x16x32_bf16 v[68:71], v[196:199], v[188:191], v[68:71]
	v_mfma_f32_16x16x32_bf16 v[64:67], v[212:215], v[188:191], v[64:67]
	s_mov_b32 m0, s29
	s_mov_b64 s[100:101], s[22:23]
	s_barrier
	ds_read_b128 v[150:153], v159 offset:16384
	ds_read_b128 v[160:163], v159 offset:17408
	ds_read_b128 v[164:167], v159 offset:18432
	ds_read_b128 v[168:171], v159 offset:19456
	ds_read_b128 v[172:175], v159 offset:20480
	ds_read_b128 v[180:183], v159 offset:21504
	ds_read_b128 v[184:187], v159 offset:22528
	ds_read_b128 v[188:191], v159 offset:23552
	global_load_lds_dwordx4 v178, s[22:23]
	s_mov_b64 s[100:101], s[22:23]
	s_mov_b32 m0, s30
	s_nop 0
	global_load_lds_dwordx4 v144, s[22:23]
	s_barrier
	s_waitcnt lgkmcnt(0)
	s_waitcnt lgkmcnt(0)
	v_mfma_f32_16x16x32_bf16 v[60:63], v[128:131], v[150:153], v[60:63]
	v_mfma_f32_16x16x32_bf16 v[56:59], v[136:139], v[150:153], v[56:59]
	v_mfma_f32_16x16x32_bf16 v[44:47], v[128:131], v[164:167], v[44:47]
	v_mfma_f32_16x16x32_bf16 v[40:43], v[136:139], v[164:167], v[40:43]
	v_mfma_f32_16x16x32_bf16 v[28:31], v[128:131], v[172:175], v[28:31]
	v_mfma_f32_16x16x32_bf16 v[24:27], v[136:139], v[172:175], v[24:27]
	v_mfma_f32_16x16x32_bf16 v[12:15], v[128:131], v[184:187], v[12:15]
	v_mfma_f32_16x16x32_bf16 v[8:11], v[136:139], v[184:187], v[8:11]
	v_mfma_f32_16x16x32_bf16 v[60:63], v[132:135], v[160:163], v[60:63]
	v_mfma_f32_16x16x32_bf16 v[56:59], v[140:143], v[160:163], v[56:59]
	v_mfma_f32_16x16x32_bf16 v[44:47], v[132:135], v[168:171], v[44:47]
	v_mfma_f32_16x16x32_bf16 v[40:43], v[140:143], v[168:171], v[40:43]
	v_mfma_f32_16x16x32_bf16 v[28:31], v[132:135], v[180:183], v[28:31]
	v_mfma_f32_16x16x32_bf16 v[24:27], v[140:143], v[180:183], v[24:27]
	v_mfma_f32_16x16x32_bf16 v[12:15], v[132:135], v[188:191], v[12:15]
	v_mfma_f32_16x16x32_bf16 v[8:11], v[140:143], v[188:191], v[8:11]
	s_barrier
	s_add_u32 s16, s20, 0x80000
	s_addc_u32 s17, s21, 0
	s_add_i32 s66, s67, s28
	s_mov_b32 m0, s66
	s_nop 0
	global_load_lds_dwordx4 v178, s[16:17]
	s_add_i32 m0, s66, 0x2000
	s_nop 0
	global_load_lds_dwordx4 v144, s[16:17]
	s_waitcnt vmcnt(6)
	s_barrier
	v_mfma_f32_16x16x32_bf16 v[52:55], v[192:195], v[150:153], v[52:55]
	v_mfma_f32_16x16x32_bf16 v[48:51], v[204:207], v[150:153], v[48:51]
	v_mfma_f32_16x16x32_bf16 v[36:39], v[192:195], v[164:167], v[36:39]
	v_mfma_f32_16x16x32_bf16 v[32:35], v[204:207], v[164:167], v[32:35]
	v_mfma_f32_16x16x32_bf16 v[20:23], v[192:195], v[172:175], v[20:23]
	v_mfma_f32_16x16x32_bf16 v[16:19], v[204:207], v[172:175], v[16:19]
	v_mfma_f32_16x16x32_bf16 v[4:7], v[192:195], v[184:187], v[4:7]
	v_mfma_f32_16x16x32_bf16 v[0:3], v[204:207], v[184:187], v[0:3]
	v_mfma_f32_16x16x32_bf16 v[52:55], v[196:199], v[160:163], v[52:55]
	v_mfma_f32_16x16x32_bf16 v[48:51], v[212:215], v[160:163], v[48:51]
	v_mfma_f32_16x16x32_bf16 v[36:39], v[196:199], v[168:171], v[36:39]
	v_mfma_f32_16x16x32_bf16 v[32:35], v[212:215], v[168:171], v[32:35]
	v_mfma_f32_16x16x32_bf16 v[20:23], v[196:199], v[180:183], v[20:23]
	v_mfma_f32_16x16x32_bf16 v[16:19], v[212:215], v[180:183], v[16:19]
	v_mfma_f32_16x16x32_bf16 v[4:7], v[196:199], v[188:191], v[4:7]
	v_mfma_f32_16x16x32_bf16 v[0:3], v[212:215], v[188:191], v[0:3]
	s_add_i32 s66, 0, 0x18000
	v_add_u32_e32 v140, s66, v157
	s_barrier
	ds_read_b128 v[128:131], v140
	ds_read_b128 v[132:135], v140 offset:1024
	ds_read_b128 v[136:139], v140 offset:2048
	ds_read_b128 v[140:143], v140 offset:3072
	s_add_u32 s16, s22, 0x80000
	s_addc_u32 s17, s23, 0
	s_mov_b32 m0, s31
	ds_read_b128 v[150:153], v159 offset:32768
	ds_read_b128 v[160:163], v159 offset:33792
	ds_read_b128 v[164:167], v159 offset:34816
	ds_read_b128 v[168:171], v159 offset:35840
	ds_read_b128 v[172:175], v159 offset:36864
	ds_read_b128 v[180:183], v159 offset:37888
	ds_read_b128 v[184:187], v159 offset:38912
	ds_read_b128 v[188:191], v159 offset:39936
	global_load_lds_dwordx4 v178, s[16:17]
	s_mov_b32 m0, s34
	s_nop 0
	global_load_lds_dwordx4 v144, s[16:17]
	s_waitcnt lgkmcnt(8)
	s_barrier
	s_waitcnt lgkmcnt(0)
	s_waitcnt lgkmcnt(0)
	v_mfma_f32_16x16x32_bf16 v[124:127], v[128:131], v[150:153], v[124:127]
	v_mfma_f32_16x16x32_bf16 v[120:123], v[136:139], v[150:153], v[120:123]
	v_mfma_f32_16x16x32_bf16 v[108:111], v[128:131], v[164:167], v[108:111]
	v_mfma_f32_16x16x32_bf16 v[104:107], v[136:139], v[164:167], v[104:107]
	v_mfma_f32_16x16x32_bf16 v[92:95], v[128:131], v[172:175], v[92:95]
	v_mfma_f32_16x16x32_bf16 v[88:91], v[136:139], v[172:175], v[88:91]
	v_mfma_f32_16x16x32_bf16 v[76:79], v[128:131], v[184:187], v[76:79]
	v_mfma_f32_16x16x32_bf16 v[72:75], v[136:139], v[184:187], v[72:75]
	v_mfma_f32_16x16x32_bf16 v[124:127], v[132:135], v[160:163], v[124:127]
	v_mfma_f32_16x16x32_bf16 v[120:123], v[140:143], v[160:163], v[120:123]
	v_mfma_f32_16x16x32_bf16 v[108:111], v[132:135], v[168:171], v[108:111]
	v_mfma_f32_16x16x32_bf16 v[104:107], v[140:143], v[168:171], v[104:107]
	v_mfma_f32_16x16x32_bf16 v[92:95], v[132:135], v[180:183], v[92:95]
	v_mfma_f32_16x16x32_bf16 v[88:91], v[140:143], v[180:183], v[88:91]
	v_mfma_f32_16x16x32_bf16 v[76:79], v[132:135], v[188:191], v[76:79]
	v_mfma_f32_16x16x32_bf16 v[72:75], v[140:143], v[188:191], v[72:75]
	s_barrier
	s_add_i32 s22, 0, 0x1c000
	s_add_i32 s16, s66, s28
	v_add_u32_e32 v212, s22, v157
	s_add_i32 m0, s16, 0xffffff80
	ds_read_b128 v[192:195], v212
	ds_read_b128 v[196:199], v212 offset:1024
	ds_read_b128 v[204:207], v212 offset:2048
	ds_read_b128 v[212:215], v212 offset:3072
	global_load_lds_dwordx4 v178, s[20:21] offset:128
	s_add_i32 m0, s16, 0x1f80
	s_nop 0
	global_load_lds_dwordx4 v144, s[20:21] offset:128
	s_barrier
	s_waitcnt lgkmcnt(0)
	s_waitcnt lgkmcnt(0)
	v_mfma_f32_16x16x32_bf16 v[116:119], v[192:195], v[150:153], v[116:119]
	v_mfma_f32_16x16x32_bf16 v[112:115], v[204:207], v[150:153], v[112:115]
	v_mfma_f32_16x16x32_bf16 v[100:103], v[192:195], v[164:167], v[100:103]
	v_mfma_f32_16x16x32_bf16 v[96:99], v[204:207], v[164:167], v[96:99]
	v_mfma_f32_16x16x32_bf16 v[84:87], v[192:195], v[172:175], v[84:87]
	v_mfma_f32_16x16x32_bf16 v[80:83], v[204:207], v[172:175], v[80:83]
	v_mfma_f32_16x16x32_bf16 v[68:71], v[192:195], v[184:187], v[68:71]
	v_mfma_f32_16x16x32_bf16 v[64:67], v[204:207], v[184:187], v[64:67]
	v_mfma_f32_16x16x32_bf16 v[116:119], v[196:199], v[160:163], v[116:119]
	v_mfma_f32_16x16x32_bf16 v[112:115], v[212:215], v[160:163], v[112:115]
	v_mfma_f32_16x16x32_bf16 v[100:103], v[196:199], v[168:171], v[100:103]
	v_mfma_f32_16x16x32_bf16 v[96:99], v[212:215], v[168:171], v[96:99]
	v_mfma_f32_16x16x32_bf16 v[84:87], v[196:199], v[180:183], v[84:87]
	v_mfma_f32_16x16x32_bf16 v[80:83], v[212:215], v[180:183], v[80:83]
	v_mfma_f32_16x16x32_bf16 v[68:71], v[196:199], v[188:191], v[68:71]
	v_mfma_f32_16x16x32_bf16 v[64:67], v[212:215], v[188:191], v[64:67]
	s_add_i32 m0, s56, 0xffffff80
	s_barrier
	ds_read_b128 v[150:153], v159 offset:49152
	ds_read_b128 v[160:163], v159 offset:50176
	ds_read_b128 v[164:167], v159 offset:51200
	ds_read_b128 v[168:171], v159 offset:52224
	ds_read_b128 v[172:175], v159 offset:53248
	ds_read_b128 v[180:183], v159 offset:54272
	ds_read_b128 v[184:187], v159 offset:55296
	ds_read_b128 v[188:191], v159 offset:56320
	global_load_lds_dwordx4 v178, s[100:101] offset:128
	s_add_i32 m0, s57, 0xffffff80
	s_nop 0
	global_load_lds_dwordx4 v144, s[100:101] offset:128
	s_barrier
	s_waitcnt lgkmcnt(0)
	s_waitcnt lgkmcnt(0)
	v_mfma_f32_16x16x32_bf16 v[60:63], v[128:131], v[150:153], v[60:63]
	v_mfma_f32_16x16x32_bf16 v[56:59], v[136:139], v[150:153], v[56:59]
	v_mfma_f32_16x16x32_bf16 v[44:47], v[128:131], v[164:167], v[44:47]
	v_mfma_f32_16x16x32_bf16 v[40:43], v[136:139], v[164:167], v[40:43]
	v_mfma_f32_16x16x32_bf16 v[28:31], v[128:131], v[172:175], v[28:31]
	v_mfma_f32_16x16x32_bf16 v[24:27], v[136:139], v[172:175], v[24:27]
	v_mfma_f32_16x16x32_bf16 v[12:15], v[128:131], v[184:187], v[12:15]
	v_mfma_f32_16x16x32_bf16 v[8:11], v[136:139], v[184:187], v[8:11]
	v_mfma_f32_16x16x32_bf16 v[60:63], v[132:135], v[160:163], v[60:63]
	v_mfma_f32_16x16x32_bf16 v[56:59], v[140:143], v[160:163], v[56:59]
	v_mfma_f32_16x16x32_bf16 v[44:47], v[132:135], v[168:171], v[44:47]
	v_mfma_f32_16x16x32_bf16 v[40:43], v[140:143], v[168:171], v[40:43]
	v_mfma_f32_16x16x32_bf16 v[28:31], v[132:135], v[180:183], v[28:31]
	v_mfma_f32_16x16x32_bf16 v[24:27], v[140:143], v[180:183], v[24:27]
	v_mfma_f32_16x16x32_bf16 v[12:15], v[132:135], v[188:191], v[12:15]
	v_mfma_f32_16x16x32_bf16 v[8:11], v[140:143], v[188:191], v[8:11]
	s_barrier
	s_add_u32 s16, s20, 0x80080
	s_addc_u32 s17, s21, 0
	s_add_i32 s20, s22, s28
	s_mov_b32 m0, s20
	s_nop 0
	global_load_lds_dwordx4 v178, s[16:17]
	s_add_i32 m0, s20, 0x2000
	s_nop 0
	global_load_lds_dwordx4 v144, s[16:17]
	s_waitcnt vmcnt(6)
	s_barrier
	v_mfma_f32_16x16x32_bf16 v[52:55], v[192:195], v[150:153], v[52:55]
	v_mfma_f32_16x16x32_bf16 v[48:51], v[204:207], v[150:153], v[48:51]
	v_mfma_f32_16x16x32_bf16 v[36:39], v[192:195], v[164:167], v[36:39]
	v_mfma_f32_16x16x32_bf16 v[32:35], v[204:207], v[164:167], v[32:35]
	v_mfma_f32_16x16x32_bf16 v[20:23], v[192:195], v[172:175], v[20:23]
	v_mfma_f32_16x16x32_bf16 v[16:19], v[204:207], v[172:175], v[16:19]
	v_mfma_f32_16x16x32_bf16 v[4:7], v[192:195], v[184:187], v[4:7]
	v_mfma_f32_16x16x32_bf16 v[0:3], v[204:207], v[184:187], v[0:3]
	v_mfma_f32_16x16x32_bf16 v[52:55], v[196:199], v[160:163], v[52:55]
	v_mfma_f32_16x16x32_bf16 v[48:51], v[212:215], v[160:163], v[48:51]
	v_mfma_f32_16x16x32_bf16 v[36:39], v[196:199], v[168:171], v[36:39]
	v_mfma_f32_16x16x32_bf16 v[32:35], v[212:215], v[168:171], v[32:35]
	v_mfma_f32_16x16x32_bf16 v[20:23], v[196:199], v[180:183], v[20:23]
	v_mfma_f32_16x16x32_bf16 v[16:19], v[212:215], v[180:183], v[16:19]
	v_mfma_f32_16x16x32_bf16 v[4:7], v[196:199], v[188:191], v[4:7]
	v_mfma_f32_16x16x32_bf16 v[0:3], v[212:215], v[188:191], v[0:3]
	s_add_i32 s63, s63, 2
	s_add_u32 s5, s5, 0x100
	s_addc_u32 s62, s62, 0
	s_cmp_gt_u32 s63, 29
	s_mov_b64 s[16:17], s[18:19]
	s_barrier
	s_cbranch_scc0 .LBB0_1077
	s_lshl_b32 s5, s60, 8
	s_add_i32 s12, s5, 0xfffff000
	s_ashr_i32 s12, s12, 11
	s_add_i32 s12, s12, 1
	s_cmp_lt_i32 s60, 16
	s_cselect_b32 s12, 0, s12
	v_add_u32_e32 v154, s5, v156
	v_lshl_or_b32 v152, s61, 8, v158
	s_mul_hi_i32 s15, s12, 0xc000
	s_mul_i32 s14, s12, 0xc000
	v_readlane_b32 s12, v254, 59
	v_readlane_b32 s13, v254, 63
	v_ashrrev_i32_e32 v155, 31, v154
	s_cselect_b32 s13, s12, s13
	v_readlane_b32 s12, v254, 61
	v_readlane_b32 s16, v255, 1
	v_ashrrev_i32_e32 v153, 31, v152
	v_lshlrev_b64 v[150:151], 11, v[154:155]
	s_cselect_b32 s12, s12, s16
	s_add_u32 s14, s35, s14
	v_lshl_add_u64 v[150:151], v[150:151], 0, v[152:153]
	s_addc_u32 s15, s39, s15
	v_lshlrev_b64 v[150:151], 2, v[150:151]
	v_lshl_add_u64 v[128:129], v[152:153], 2, s[14:15]
	v_lshl_add_u64 v[166:167], s[12:13], 0, v[150:151]
	global_load_dwordx4 v[140:143], v[128:129], off
	global_load_dwordx4 v[136:139], v[128:129], off offset:64
	global_load_dwordx4 v[132:135], v[128:129], off offset:512
	s_nop 0
	global_load_dwordx4 v[128:131], v[128:129], off offset:576
	v_readlane_b32 s68, v252, 37
	v_readlane_b32 s82, v252, 51
	v_readlane_b32 s83, v252, 52
	s_and_b64 vcc, exec, s[10:11]
	s_mov_b32 s61, s59
	s_mov_b32 s60, s4
	s_mov_b64 s[18:19], s[6:7]
	s_mov_b64 s[16:17], s[8:9]
	v_readlane_b32 s69, v252, 38
	v_readlane_b32 s70, v252, 39
	v_readlane_b32 s71, v252, 40
	v_readlane_b32 s72, v252, 41
	v_readlane_b32 s73, v252, 42
	v_readlane_b32 s74, v252, 43
	v_readlane_b32 s75, v252, 44
	v_readlane_b32 s76, v252, 45
	v_readlane_b32 s77, v252, 46
	v_readlane_b32 s78, v252, 47
	v_readlane_b32 s79, v252, 48
	v_readlane_b32 s80, v252, 49
	v_readlane_b32 s81, v252, 50
	s_nop 4
	v_mov_b32_e32 v145, v150
	v_add_u32_e32 v164, 0x20000, v145
	v_add_u32_e32 v165, 0x40000, v145
	v_add_u32_e32 v176, 0x60000, v145
	v_add_u32_e32 v177, 0x100000, v145
	v_add_u32_e32 v223, 0x120000, v145
	v_add_u32_e32 v248, 0x140000, v145
	v_add_u32_e32 v249, 0x160000, v145
	global_load_dwordx4 v[160:163], v145, s[12:13]
	global_load_dwordx4 v[168:171], v145, s[12:13] offset:64
	global_load_dwordx4 v[172:175], v145, s[12:13] offset:512
	global_load_dwordx4 v[180:183], v145, s[12:13] offset:576
	global_load_dwordx4 v[184:187], v164, s[12:13]
	global_load_dwordx4 v[188:191], v164, s[12:13] offset:64
	global_load_dwordx4 v[192:195], v164, s[12:13] offset:512
	global_load_dwordx4 v[196:199], v164, s[12:13] offset:576
	global_load_dwordx4 v[204:207], v165, s[12:13]
	global_load_dwordx4 v[212:215], v165, s[12:13] offset:64
	global_load_dwordx4 v[224:227], v165, s[12:13] offset:512
	global_load_dwordx4 v[228:231], v165, s[12:13] offset:576
	global_load_dwordx4 v[232:235], v176, s[12:13]
	global_load_dwordx4 v[236:239], v176, s[12:13] offset:64
	global_load_dwordx4 v[240:243], v176, s[12:13] offset:512
	global_load_dwordx4 v[244:247], v176, s[12:13] offset:576
	s_waitcnt vmcnt(15)
	v_pk_fma_f32 v[126:127], v[126:127], v[142:143], v[162:163]
	v_pk_fma_f32 v[124:125], v[124:125], v[140:141], v[160:161]
	global_store_dwordx4 v145, v[124:127], s[82:83]
	global_load_dwordx4 v[160:163], v177, s[12:13]
	s_waitcnt vmcnt(16)
	v_pk_fma_f32 v[122:123], v[122:123], v[138:139], v[170:171]
	v_pk_fma_f32 v[120:121], v[120:121], v[136:137], v[168:169]
	global_store_dwordx4 v145, v[120:123], s[82:83] offset:64
	global_load_dwordx4 v[168:171], v177, s[12:13] offset:64
	s_waitcnt vmcnt(17)
	v_pk_fma_f32 v[118:119], v[118:119], v[134:135], v[174:175]
	v_pk_fma_f32 v[116:117], v[116:117], v[132:133], v[172:173]
	global_store_dwordx4 v145, v[116:119], s[82:83] offset:512
	global_load_dwordx4 v[172:175], v177, s[12:13] offset:512
	s_waitcnt vmcnt(18)
	v_pk_fma_f32 v[114:115], v[114:115], v[130:131], v[182:183]
	v_pk_fma_f32 v[112:113], v[112:113], v[128:129], v[180:181]
	global_store_dwordx4 v145, v[112:115], s[82:83] offset:576
	global_load_dwordx4 v[180:183], v177, s[12:13] offset:576
	s_waitcnt vmcnt(19)
	v_pk_fma_f32 v[110:111], v[110:111], v[142:143], v[186:187]
	v_pk_fma_f32 v[108:109], v[108:109], v[140:141], v[184:185]
	global_store_dwordx4 v164, v[108:111], s[82:83]
	global_load_dwordx4 v[184:187], v223, s[12:13]
	s_waitcnt vmcnt(20)
	v_pk_fma_f32 v[106:107], v[106:107], v[138:139], v[190:191]
	v_pk_fma_f32 v[104:105], v[104:105], v[136:137], v[188:189]
	global_store_dwordx4 v164, v[104:107], s[82:83] offset:64
	global_load_dwordx4 v[188:191], v223, s[12:13] offset:64
	s_waitcnt vmcnt(21)
	v_pk_fma_f32 v[102:103], v[102:103], v[134:135], v[194:195]
	v_pk_fma_f32 v[100:101], v[100:101], v[132:133], v[192:193]
	global_store_dwordx4 v164, v[100:103], s[82:83] offset:512
	global_load_dwordx4 v[192:195], v223, s[12:13] offset:512
	s_waitcnt vmcnt(22)
	v_pk_fma_f32 v[98:99], v[98:99], v[130:131], v[198:199]
	v_pk_fma_f32 v[96:97], v[96:97], v[128:129], v[196:197]
	global_store_dwordx4 v164, v[96:99], s[82:83] offset:576
	global_load_dwordx4 v[196:199], v223, s[12:13] offset:576
	s_waitcnt vmcnt(23)
	v_pk_fma_f32 v[94:95], v[94:95], v[142:143], v[206:207]
	v_pk_fma_f32 v[92:93], v[92:93], v[140:141], v[204:205]
	global_store_dwordx4 v165, v[92:95], s[82:83]
	global_load_dwordx4 v[204:207], v248, s[12:13]
	s_waitcnt vmcnt(24)
	v_pk_fma_f32 v[90:91], v[90:91], v[138:139], v[214:215]
	v_pk_fma_f32 v[88:89], v[88:89], v[136:137], v[212:213]
	global_store_dwordx4 v165, v[88:91], s[82:83] offset:64
	global_load_dwordx4 v[212:215], v248, s[12:13] offset:64
	s_waitcnt vmcnt(25)
	v_pk_fma_f32 v[86:87], v[86:87], v[134:135], v[226:227]
	v_pk_fma_f32 v[84:85], v[84:85], v[132:133], v[224:225]
	global_store_dwordx4 v165, v[84:87], s[82:83] offset:512
	global_load_dwordx4 v[224:227], v248, s[12:13] offset:512
	s_waitcnt vmcnt(26)
	v_pk_fma_f32 v[82:83], v[82:83], v[130:131], v[230:231]
	v_pk_fma_f32 v[80:81], v[80:81], v[128:129], v[228:229]
	global_store_dwordx4 v165, v[80:83], s[82:83] offset:576
	global_load_dwordx4 v[228:231], v248, s[12:13] offset:576
	s_waitcnt vmcnt(27)
	v_pk_fma_f32 v[78:79], v[78:79], v[142:143], v[234:235]
	v_pk_fma_f32 v[76:77], v[76:77], v[140:141], v[232:233]
	global_store_dwordx4 v176, v[76:79], s[82:83]
	global_load_dwordx4 v[232:235], v249, s[12:13]
	s_waitcnt vmcnt(28)
	v_pk_fma_f32 v[74:75], v[74:75], v[138:139], v[238:239]
	v_pk_fma_f32 v[72:73], v[72:73], v[136:137], v[236:237]
	global_store_dwordx4 v176, v[72:75], s[82:83] offset:64
	global_load_dwordx4 v[236:239], v249, s[12:13] offset:64
	s_waitcnt vmcnt(29)
	v_pk_fma_f32 v[70:71], v[70:71], v[134:135], v[242:243]
	v_pk_fma_f32 v[68:69], v[68:69], v[132:133], v[240:241]
	global_store_dwordx4 v176, v[68:71], s[82:83] offset:512
	global_load_dwordx4 v[240:243], v249, s[12:13] offset:512
	s_waitcnt vmcnt(30)
	v_pk_fma_f32 v[66:67], v[66:67], v[130:131], v[246:247]
	v_pk_fma_f32 v[64:65], v[64:65], v[128:129], v[244:245]
	global_store_dwordx4 v176, v[64:67], s[82:83] offset:576
	global_load_dwordx4 v[244:247], v249, s[12:13] offset:576
	s_waitcnt vmcnt(30)
	v_pk_fma_f32 v[62:63], v[62:63], v[142:143], v[162:163]
	v_pk_fma_f32 v[60:61], v[60:61], v[140:141], v[160:161]
	global_store_dwordx4 v177, v[60:63], s[82:83]
	s_waitcnt vmcnt(29)
	v_pk_fma_f32 v[58:59], v[58:59], v[138:139], v[170:171]
	v_pk_fma_f32 v[56:57], v[56:57], v[136:137], v[168:169]
	global_store_dwordx4 v177, v[56:59], s[82:83] offset:64
	s_waitcnt vmcnt(28)
	v_pk_fma_f32 v[54:55], v[54:55], v[134:135], v[174:175]
	v_pk_fma_f32 v[52:53], v[52:53], v[132:133], v[172:173]
	global_store_dwordx4 v177, v[52:55], s[82:83] offset:512
	s_waitcnt vmcnt(27)
	v_pk_fma_f32 v[50:51], v[50:51], v[130:131], v[182:183]
	v_pk_fma_f32 v[48:49], v[48:49], v[128:129], v[180:181]
	global_store_dwordx4 v177, v[48:51], s[82:83] offset:576
	s_waitcnt vmcnt(26)
	v_pk_fma_f32 v[46:47], v[46:47], v[142:143], v[186:187]
	v_pk_fma_f32 v[44:45], v[44:45], v[140:141], v[184:185]
	global_store_dwordx4 v223, v[44:47], s[82:83]
	s_waitcnt vmcnt(25)
	v_pk_fma_f32 v[42:43], v[42:43], v[138:139], v[190:191]
	v_pk_fma_f32 v[40:41], v[40:41], v[136:137], v[188:189]
	global_store_dwordx4 v223, v[40:43], s[82:83] offset:64
	s_waitcnt vmcnt(24)
	v_pk_fma_f32 v[38:39], v[38:39], v[134:135], v[194:195]
	v_pk_fma_f32 v[36:37], v[36:37], v[132:133], v[192:193]
	global_store_dwordx4 v223, v[36:39], s[82:83] offset:512
	s_waitcnt vmcnt(23)
	v_pk_fma_f32 v[34:35], v[34:35], v[130:131], v[198:199]
	v_pk_fma_f32 v[32:33], v[32:33], v[128:129], v[196:197]
	global_store_dwordx4 v223, v[32:35], s[82:83] offset:576
	s_waitcnt vmcnt(22)
	v_pk_fma_f32 v[30:31], v[30:31], v[142:143], v[206:207]
	v_pk_fma_f32 v[28:29], v[28:29], v[140:141], v[204:205]
	global_store_dwordx4 v248, v[28:31], s[82:83]
	s_waitcnt vmcnt(21)
	v_pk_fma_f32 v[26:27], v[26:27], v[138:139], v[214:215]
	v_pk_fma_f32 v[24:25], v[24:25], v[136:137], v[212:213]
	global_store_dwordx4 v248, v[24:27], s[82:83] offset:64
	s_waitcnt vmcnt(20)
	v_pk_fma_f32 v[22:23], v[22:23], v[134:135], v[226:227]
	v_pk_fma_f32 v[20:21], v[20:21], v[132:133], v[224:225]
	global_store_dwordx4 v248, v[20:23], s[82:83] offset:512
	s_waitcnt vmcnt(19)
	v_pk_fma_f32 v[18:19], v[18:19], v[130:131], v[230:231]
	v_pk_fma_f32 v[16:17], v[16:17], v[128:129], v[228:229]
	global_store_dwordx4 v248, v[16:19], s[82:83] offset:576
	s_waitcnt vmcnt(18)
	v_pk_fma_f32 v[14:15], v[14:15], v[142:143], v[234:235]
	v_pk_fma_f32 v[12:13], v[12:13], v[140:141], v[232:233]
	global_store_dwordx4 v249, v[12:15], s[82:83]
	s_waitcnt vmcnt(17)
	v_pk_fma_f32 v[10:11], v[10:11], v[138:139], v[238:239]
	v_pk_fma_f32 v[8:9], v[8:9], v[136:137], v[236:237]
	global_store_dwordx4 v249, v[8:11], s[82:83] offset:64
	s_waitcnt vmcnt(16)
	v_pk_fma_f32 v[6:7], v[6:7], v[134:135], v[242:243]
	v_pk_fma_f32 v[4:5], v[4:5], v[132:133], v[240:241]
	global_store_dwordx4 v249, v[4:7], s[82:83] offset:512
	s_waitcnt vmcnt(15)
	v_pk_fma_f32 v[2:3], v[2:3], v[130:131], v[246:247]
	v_pk_fma_f32 v[0:1], v[0:1], v[128:129], v[244:245]
	global_store_dwordx4 v249, v[0:3], s[82:83] offset:576
	s_mov_b64 s[14:15], 0x160000
	s_cbranch_vccz .LBB0_1074
	s_waitcnt vmcnt(0)
	s_mov_b32 s4, s86
	s_cmp_gt_u32 s4, 3
	s_mov_b32 s34, 0x10000
	s_movk_i32 s57, 0x404
	s_cbranch_scc1 .LBB0_1081
	s_barrier

.LBB0_1363:
	s_add_u32 s16, s14, 0x100
	s_addc_u32 s17, s15, 0
	s_add_i32 s68, 0, 0x10000
	v_add_u32_e32 v76, s68, v153
	ds_read_b128 v[48:51], v76
	ds_read_b128 v[68:71], v76 offset:1024
	ds_read_b128 v[72:75], v76 offset:2048
	ds_read_b128 v[76:79], v76 offset:3072
	s_cmpk_eq_i32 s67, 0x52
	s_cselect_b32 s21, s11, s17
	s_cselect_b32 s20, s10, s16
	s_cselect_b32 s19, s13, s66
	s_cselect_b32 s18, s12, s63
	v_lshl_add_u64 v[150:151], s[14:15], 0, v[148:149]
	s_add_i32 m0, s29, 0xc000
	ds_read_b128 v[156:159], v155
	ds_read_b128 v[160:163], v155 offset:1024
	ds_read_b128 v[164:167], v155 offset:2048
	ds_read_b128 v[168:171], v155 offset:3072
	ds_read_b128 v[172:175], v155 offset:4096
	ds_read_b128 v[180:183], v155 offset:5120
	ds_read_b128 v[184:187], v155 offset:6144
	ds_read_b128 v[188:191], v155 offset:7168
	global_load_lds_dwordx4 v[150:151], off
	v_lshl_add_u64 v[150:151], s[14:15], 0, v[146:147]
	s_add_i32 m0, s29, 0xe000
	s_nop 0
	global_load_lds_dwordx4 v[150:151], off
	s_waitcnt lgkmcnt(8)
	s_barrier
	s_waitcnt lgkmcnt(0)
	s_waitcnt lgkmcnt(0)
	v_mfma_f32_16x16x32_bf16 v[140:143], v[48:51], v[156:159], v[140:143]
	v_mfma_f32_16x16x32_bf16 v[136:139], v[72:75], v[156:159], v[136:139]
	v_mfma_f32_16x16x32_bf16 v[124:127], v[48:51], v[164:167], v[124:127]
	v_mfma_f32_16x16x32_bf16 v[120:123], v[72:75], v[164:167], v[120:123]
	v_mfma_f32_16x16x32_bf16 v[116:119], v[48:51], v[172:175], v[116:119]
	v_mfma_f32_16x16x32_bf16 v[112:115], v[72:75], v[172:175], v[112:115]
	v_mfma_f32_16x16x32_bf16 v[100:103], v[48:51], v[184:187], v[100:103]
	v_mfma_f32_16x16x32_bf16 v[96:99], v[72:75], v[184:187], v[96:99]
	v_mfma_f32_16x16x32_bf16 v[140:143], v[68:71], v[160:163], v[140:143]
	v_mfma_f32_16x16x32_bf16 v[136:139], v[76:79], v[160:163], v[136:139]
	v_mfma_f32_16x16x32_bf16 v[124:127], v[68:71], v[168:171], v[124:127]
	v_mfma_f32_16x16x32_bf16 v[120:123], v[76:79], v[168:171], v[120:123]
	v_mfma_f32_16x16x32_bf16 v[116:119], v[68:71], v[180:183], v[116:119]
	v_mfma_f32_16x16x32_bf16 v[112:115], v[76:79], v[180:183], v[112:115]
	v_mfma_f32_16x16x32_bf16 v[100:103], v[68:71], v[188:191], v[100:103]
	v_mfma_f32_16x16x32_bf16 v[96:99], v[76:79], v[188:191], v[96:99]
	s_barrier
	s_add_i32 s69, 0, 0x14000
	v_add_u32_e32 v150, s69, v153
	s_add_i32 s14, s68, s28
	ds_read_b128 v[192:195], v150
	ds_read_b128 v[196:199], v150 offset:1024
	ds_read_b128 v[204:207], v150 offset:2048
	ds_read_b128 v[212:215], v150 offset:3072
	s_mov_b32 m0, s14
	global_load_lds_dwordx4 v178, s[18:19]
	s_add_i32 m0, s14, 0x2000
	s_nop 0
	global_load_lds_dwordx4 v144, s[18:19]
	s_barrier
	s_waitcnt lgkmcnt(0)
	s_waitcnt lgkmcnt(0)
	v_mfma_f32_16x16x32_bf16 v[132:135], v[192:195], v[156:159], v[132:135]
	v_mfma_f32_16x16x32_bf16 v[128:131], v[204:207], v[156:159], v[128:131]
	v_mfma_f32_16x16x32_bf16 v[108:111], v[192:195], v[164:167], v[108:111]
	v_mfma_f32_16x16x32_bf16 v[104:107], v[204:207], v[164:167], v[104:107]
	v_mfma_f32_16x16x32_bf16 v[92:95], v[192:195], v[172:175], v[92:95]
	v_mfma_f32_16x16x32_bf16 v[88:91], v[204:207], v[172:175], v[88:91]
	v_mfma_f32_16x16x32_bf16 v[84:87], v[192:195], v[184:187], v[84:87]
	v_mfma_f32_16x16x32_bf16 v[80:83], v[204:207], v[184:187], v[80:83]
	v_mfma_f32_16x16x32_bf16 v[132:135], v[196:199], v[160:163], v[132:135]
	v_mfma_f32_16x16x32_bf16 v[128:131], v[212:215], v[160:163], v[128:131]
	v_mfma_f32_16x16x32_bf16 v[108:111], v[196:199], v[168:171], v[108:111]
	v_mfma_f32_16x16x32_bf16 v[104:107], v[212:215], v[168:171], v[104:107]
	v_mfma_f32_16x16x32_bf16 v[92:95], v[196:199], v[180:183], v[92:95]
	v_mfma_f32_16x16x32_bf16 v[88:91], v[212:215], v[180:183], v[88:91]
	v_mfma_f32_16x16x32_bf16 v[84:87], v[196:199], v[188:191], v[84:87]
	v_mfma_f32_16x16x32_bf16 v[80:83], v[212:215], v[188:191], v[80:83]
	s_mov_b32 m0, s29
	s_mov_b64 s[100:101], s[20:21]
	s_barrier
	ds_read_b128 v[156:159], v155 offset:16384
	ds_read_b128 v[160:163], v155 offset:17408
	ds_read_b128 v[164:167], v155 offset:18432
	ds_read_b128 v[168:171], v155 offset:19456
	ds_read_b128 v[172:175], v155 offset:20480
	ds_read_b128 v[180:183], v155 offset:21504
	ds_read_b128 v[184:187], v155 offset:22528
	ds_read_b128 v[188:191], v155 offset:23552
	global_load_lds_dwordx4 v178, s[20:21]
	s_mov_b64 s[100:101], s[20:21]
	s_mov_b32 m0, s30
	s_nop 0
	global_load_lds_dwordx4 v144, s[20:21]
	s_barrier
	s_waitcnt lgkmcnt(0)
	s_waitcnt lgkmcnt(0)
	v_mfma_f32_16x16x32_bf16 v[64:67], v[48:51], v[156:159], v[64:67]
	v_mfma_f32_16x16x32_bf16 v[60:63], v[72:75], v[156:159], v[60:63]
	v_mfma_f32_16x16x32_bf16 v[44:47], v[48:51], v[164:167], v[44:47]
	v_mfma_f32_16x16x32_bf16 v[40:43], v[72:75], v[164:167], v[40:43]
	v_mfma_f32_16x16x32_bf16 v[28:31], v[48:51], v[172:175], v[28:31]
	v_mfma_f32_16x16x32_bf16 v[24:27], v[72:75], v[172:175], v[24:27]
	v_mfma_f32_16x16x32_bf16 v[12:15], v[48:51], v[184:187], v[12:15]
	v_mfma_f32_16x16x32_bf16 v[8:11], v[72:75], v[184:187], v[8:11]
	v_mfma_f32_16x16x32_bf16 v[64:67], v[68:71], v[160:163], v[64:67]
	v_mfma_f32_16x16x32_bf16 v[60:63], v[76:79], v[160:163], v[60:63]
	v_mfma_f32_16x16x32_bf16 v[44:47], v[68:71], v[168:171], v[44:47]
	v_mfma_f32_16x16x32_bf16 v[40:43], v[76:79], v[168:171], v[40:43]
	v_mfma_f32_16x16x32_bf16 v[28:31], v[68:71], v[180:183], v[28:31]
	v_mfma_f32_16x16x32_bf16 v[24:27], v[76:79], v[180:183], v[24:27]
	v_mfma_f32_16x16x32_bf16 v[12:15], v[68:71], v[188:191], v[12:15]
	v_mfma_f32_16x16x32_bf16 v[8:11], v[76:79], v[188:191], v[8:11]
	s_barrier
	s_add_u32 s14, s18, 0x158000
	s_addc_u32 s15, s19, 0
	s_add_i32 s68, s69, s28
	s_mov_b32 m0, s68
	s_nop 0
	global_load_lds_dwordx4 v178, s[14:15]
	s_add_i32 m0, s68, 0x2000
	s_nop 0
	global_load_lds_dwordx4 v144, s[14:15]
	s_waitcnt vmcnt(6)
	s_barrier
	v_mfma_f32_16x16x32_bf16 v[52:55], v[204:207], v[156:159], v[52:55]
	v_mfma_f32_16x16x32_bf16 v[36:39], v[192:195], v[164:167], v[36:39]
	v_mfma_f32_16x16x32_bf16 v[32:35], v[204:207], v[164:167], v[32:35]
	v_mfma_f32_16x16x32_bf16 v[20:23], v[192:195], v[172:175], v[20:23]
	v_mfma_f32_16x16x32_bf16 v[16:19], v[204:207], v[172:175], v[16:19]
	v_mfma_f32_16x16x32_bf16 v[4:7], v[192:195], v[184:187], v[4:7]
	v_mfma_f32_16x16x32_bf16 v[0:3], v[204:207], v[184:187], v[0:3]
	v_mfma_f32_16x16x32_bf16 v[48:51], v[192:195], v[156:159], v[56:59]
	v_mfma_f32_16x16x32_bf16 v[52:55], v[212:215], v[160:163], v[52:55]
	v_mfma_f32_16x16x32_bf16 v[36:39], v[196:199], v[168:171], v[36:39]
	v_mfma_f32_16x16x32_bf16 v[32:35], v[212:215], v[168:171], v[32:35]
	v_mfma_f32_16x16x32_bf16 v[20:23], v[196:199], v[180:183], v[20:23]
	v_mfma_f32_16x16x32_bf16 v[16:19], v[212:215], v[180:183], v[16:19]
	v_mfma_f32_16x16x32_bf16 v[4:7], v[196:199], v[188:191], v[4:7]
	v_mfma_f32_16x16x32_bf16 v[0:3], v[212:215], v[188:191], v[0:3]
	v_mfma_f32_16x16x32_bf16 v[48:51], v[196:199], v[160:163], v[48:51]
	s_add_i32 s68, 0, 0x18000
	v_add_u32_e32 v76, s68, v153
	s_barrier
	ds_read_b128 v[56:59], v76
	ds_read_b128 v[68:71], v76 offset:1024
	ds_read_b128 v[72:75], v76 offset:2048
	ds_read_b128 v[76:79], v76 offset:3072
	s_add_u32 s14, s20, 0x158000
	s_addc_u32 s15, s21, 0
	s_mov_b32 m0, s31
	ds_read_b128 v[156:159], v155 offset:32768
	ds_read_b128 v[160:163], v155 offset:33792
	ds_read_b128 v[164:167], v155 offset:34816
	ds_read_b128 v[168:171], v155 offset:35840
	ds_read_b128 v[172:175], v155 offset:36864
	ds_read_b128 v[180:183], v155 offset:37888
	ds_read_b128 v[184:187], v155 offset:38912
	ds_read_b128 v[188:191], v155 offset:39936
	global_load_lds_dwordx4 v178, s[14:15]
	s_mov_b32 m0, s34
	s_nop 0
	global_load_lds_dwordx4 v144, s[14:15]
	s_waitcnt lgkmcnt(8)
	s_barrier
	s_waitcnt lgkmcnt(0)
	s_waitcnt lgkmcnt(0)
	v_mfma_f32_16x16x32_bf16 v[140:143], v[56:59], v[156:159], v[140:143]
	v_mfma_f32_16x16x32_bf16 v[136:139], v[72:75], v[156:159], v[136:139]
	v_mfma_f32_16x16x32_bf16 v[124:127], v[56:59], v[164:167], v[124:127]
	v_mfma_f32_16x16x32_bf16 v[120:123], v[72:75], v[164:167], v[120:123]
	v_mfma_f32_16x16x32_bf16 v[116:119], v[56:59], v[172:175], v[116:119]
	v_mfma_f32_16x16x32_bf16 v[112:115], v[72:75], v[172:175], v[112:115]
	v_mfma_f32_16x16x32_bf16 v[100:103], v[56:59], v[184:187], v[100:103]
	v_mfma_f32_16x16x32_bf16 v[96:99], v[72:75], v[184:187], v[96:99]
	v_mfma_f32_16x16x32_bf16 v[140:143], v[68:71], v[160:163], v[140:143]
	v_mfma_f32_16x16x32_bf16 v[136:139], v[76:79], v[160:163], v[136:139]
	v_mfma_f32_16x16x32_bf16 v[124:127], v[68:71], v[168:171], v[124:127]
	v_mfma_f32_16x16x32_bf16 v[120:123], v[76:79], v[168:171], v[120:123]
	v_mfma_f32_16x16x32_bf16 v[116:119], v[68:71], v[180:183], v[116:119]
	v_mfma_f32_16x16x32_bf16 v[112:115], v[76:79], v[180:183], v[112:115]
	v_mfma_f32_16x16x32_bf16 v[100:103], v[68:71], v[188:191], v[100:103]
	v_mfma_f32_16x16x32_bf16 v[96:99], v[76:79], v[188:191], v[96:99]
	s_barrier
	s_add_i32 s20, 0, 0x1c000
	s_add_i32 s14, s68, s28
	v_add_u32_e32 v212, s20, v153
	s_add_i32 m0, s14, 0xffffff80
	ds_read_b128 v[192:195], v212
	ds_read_b128 v[196:199], v212 offset:1024
	ds_read_b128 v[204:207], v212 offset:2048
	ds_read_b128 v[212:215], v212 offset:3072
	global_load_lds_dwordx4 v178, s[18:19] offset:128
	s_add_i32 m0, s14, 0x1f80
	s_nop 0
	global_load_lds_dwordx4 v144, s[18:19] offset:128
	s_barrier
	s_waitcnt lgkmcnt(0)
	s_waitcnt lgkmcnt(0)
	v_mfma_f32_16x16x32_bf16 v[132:135], v[192:195], v[156:159], v[132:135]
	v_mfma_f32_16x16x32_bf16 v[128:131], v[204:207], v[156:159], v[128:131]
	v_mfma_f32_16x16x32_bf16 v[108:111], v[192:195], v[164:167], v[108:111]
	v_mfma_f32_16x16x32_bf16 v[104:107], v[204:207], v[164:167], v[104:107]
	v_mfma_f32_16x16x32_bf16 v[92:95], v[192:195], v[172:175], v[92:95]
	v_mfma_f32_16x16x32_bf16 v[88:91], v[204:207], v[172:175], v[88:91]
	v_mfma_f32_16x16x32_bf16 v[84:87], v[192:195], v[184:187], v[84:87]
	v_mfma_f32_16x16x32_bf16 v[80:83], v[204:207], v[184:187], v[80:83]
	v_mfma_f32_16x16x32_bf16 v[132:135], v[196:199], v[160:163], v[132:135]
	v_mfma_f32_16x16x32_bf16 v[128:131], v[212:215], v[160:163], v[128:131]
	v_mfma_f32_16x16x32_bf16 v[108:111], v[196:199], v[168:171], v[108:111]
	v_mfma_f32_16x16x32_bf16 v[104:107], v[212:215], v[168:171], v[104:107]
	v_mfma_f32_16x16x32_bf16 v[92:95], v[196:199], v[180:183], v[92:95]
	v_mfma_f32_16x16x32_bf16 v[88:91], v[212:215], v[180:183], v[88:91]
	v_mfma_f32_16x16x32_bf16 v[84:87], v[196:199], v[188:191], v[84:87]
	v_mfma_f32_16x16x32_bf16 v[80:83], v[212:215], v[188:191], v[80:83]
	s_add_i32 m0, s56, 0xffffff80
	s_barrier
	ds_read_b128 v[156:159], v155 offset:49152
	ds_read_b128 v[160:163], v155 offset:50176
	ds_read_b128 v[164:167], v155 offset:51200
	ds_read_b128 v[168:171], v155 offset:52224
	ds_read_b128 v[172:175], v155 offset:53248
	ds_read_b128 v[180:183], v155 offset:54272
	ds_read_b128 v[184:187], v155 offset:55296
	ds_read_b128 v[188:191], v155 offset:56320
	global_load_lds_dwordx4 v178, s[100:101] offset:128
	s_add_i32 m0, s57, 0xffffff80
	s_nop 0
	global_load_lds_dwordx4 v144, s[100:101] offset:128
	s_barrier
	s_waitcnt lgkmcnt(0)
	s_waitcnt lgkmcnt(0)
	v_mfma_f32_16x16x32_bf16 v[64:67], v[56:59], v[156:159], v[64:67]
	v_mfma_f32_16x16x32_bf16 v[60:63], v[72:75], v[156:159], v[60:63]
	v_mfma_f32_16x16x32_bf16 v[44:47], v[56:59], v[164:167], v[44:47]
	v_mfma_f32_16x16x32_bf16 v[40:43], v[72:75], v[164:167], v[40:43]
	v_mfma_f32_16x16x32_bf16 v[28:31], v[56:59], v[172:175], v[28:31]
	v_mfma_f32_16x16x32_bf16 v[24:27], v[72:75], v[172:175], v[24:27]
	v_mfma_f32_16x16x32_bf16 v[12:15], v[56:59], v[184:187], v[12:15]
	v_mfma_f32_16x16x32_bf16 v[8:11], v[72:75], v[184:187], v[8:11]
	v_mfma_f32_16x16x32_bf16 v[64:67], v[68:71], v[160:163], v[64:67]
	v_mfma_f32_16x16x32_bf16 v[60:63], v[76:79], v[160:163], v[60:63]
	v_mfma_f32_16x16x32_bf16 v[44:47], v[68:71], v[168:171], v[44:47]
	v_mfma_f32_16x16x32_bf16 v[40:43], v[76:79], v[168:171], v[40:43]
	v_mfma_f32_16x16x32_bf16 v[28:31], v[68:71], v[180:183], v[28:31]
	v_mfma_f32_16x16x32_bf16 v[24:27], v[76:79], v[180:183], v[24:27]
	v_mfma_f32_16x16x32_bf16 v[12:15], v[68:71], v[188:191], v[12:15]
	v_mfma_f32_16x16x32_bf16 v[8:11], v[76:79], v[188:191], v[8:11]
	s_barrier
	s_add_u32 s14, s18, 0x158080
	s_addc_u32 s15, s19, 0
	s_add_i32 s18, s20, s28
	s_mov_b32 m0, s18
	s_nop 0
	global_load_lds_dwordx4 v178, s[14:15]
	s_add_i32 m0, s18, 0x2000
	s_nop 0
	global_load_lds_dwordx4 v144, s[14:15]
	s_waitcnt vmcnt(6)
	s_barrier
	v_mfma_f32_16x16x32_bf16 v[48:51], v[192:195], v[156:159], v[48:51]
	v_mfma_f32_16x16x32_bf16 v[56:59], v[196:199], v[160:163], v[48:51]
	v_mfma_f32_16x16x32_bf16 v[48:51], v[204:207], v[156:159], v[52:55]
	v_mfma_f32_16x16x32_bf16 v[36:39], v[192:195], v[164:167], v[36:39]
	v_mfma_f32_16x16x32_bf16 v[32:35], v[204:207], v[164:167], v[32:35]
	v_mfma_f32_16x16x32_bf16 v[20:23], v[192:195], v[172:175], v[20:23]
	v_mfma_f32_16x16x32_bf16 v[16:19], v[204:207], v[172:175], v[16:19]
	v_mfma_f32_16x16x32_bf16 v[4:7], v[192:195], v[184:187], v[4:7]
	v_mfma_f32_16x16x32_bf16 v[0:3], v[204:207], v[184:187], v[0:3]
	v_mfma_f32_16x16x32_bf16 v[52:55], v[212:215], v[160:163], v[48:51]
	v_mfma_f32_16x16x32_bf16 v[36:39], v[196:199], v[168:171], v[36:39]
	v_mfma_f32_16x16x32_bf16 v[32:35], v[212:215], v[168:171], v[32:35]
	v_mfma_f32_16x16x32_bf16 v[20:23], v[196:199], v[180:183], v[20:23]
	v_mfma_f32_16x16x32_bf16 v[16:19], v[212:215], v[180:183], v[16:19]
	v_mfma_f32_16x16x32_bf16 v[4:7], v[196:199], v[188:191], v[4:7]
	v_mfma_f32_16x16x32_bf16 v[0:3], v[212:215], v[188:191], v[0:3]
	s_add_i32 s67, s67, 2
	s_add_u32 s63, s63, 0x100
	s_addc_u32 s66, s66, 0
	s_cmpk_gt_u32 s67, 0x53
	s_mov_b64 s[14:15], s[16:17]
	s_barrier
	s_cbranch_scc0 .LBB0_1363
	s_lshl_b32 s12, s61, 8
	s_add_i32 s10, s12, 0xfffff000
	s_ashr_i32 s10, s10, 11
	s_add_i32 s10, s10, 1
	s_cmp_gt_i32 s61, 15
	s_cselect_b32 s10, s10, 0
	v_add_u32_e32 v162, s12, v152
	v_lshl_or_b32 v48, s62, 8, v154
	s_mul_hi_i32 s11, s10, 0xc000
	s_mul_i32 s10, s10, 0xc000
	v_ashrrev_i32_e32 v163, 31, v162
	v_readlane_b32 s68, v252, 37
	s_add_u32 s10, s35, s10
	v_ashrrev_i32_e32 v49, 31, v48
	v_lshlrev_b64 v[150:151], 13, v[162:163]
	v_readlane_b32 s82, v252, 51
	v_readlane_b32 s83, v252, 52
	s_addc_u32 s11, s39, s11
	v_lshlrev_b64 v[160:161], 2, v[48:49]
	v_lshl_add_u64 v[150:151], s[82:83], 0, v[150:151]
	v_lshl_add_u64 v[48:49], s[10:11], 0, v[160:161]
	v_lshl_add_u64 v[150:151], v[150:151], 0, v[160:161]
	global_load_dwordx4 v[76:79], v[48:49], off
	global_load_dwordx4 v[72:75], v[48:49], off offset:64
	global_load_dwordx4 v[68:71], v[48:49], off offset:512
	s_nop 0
	global_load_dwordx4 v[48:51], v[48:49], off offset:576
	s_mov_b64 s[10:11], 0x100000
	s_mov_b32 s62, s59
	s_mov_b32 s61, s60
	s_mov_b64 s[16:17], s[6:7]
	s_mov_b64 s[14:15], s[8:9]
	v_readlane_b32 s69, v252, 38
	v_readlane_b32 s70, v252, 39
	v_readlane_b32 s71, v252, 40
	v_readlane_b32 s72, v252, 41
	v_readlane_b32 s73, v252, 42
	v_readlane_b32 s74, v252, 43
	v_readlane_b32 s75, v252, 44
	v_readlane_b32 s76, v252, 45
	v_readlane_b32 s77, v252, 46
	v_readlane_b32 s78, v252, 47
	v_readlane_b32 s79, v252, 48
	v_readlane_b32 s80, v252, 49
	v_readlane_b32 s81, v252, 50
	s_and_b64 vcc, exec, s[4:5]
	s_nop 4
	v_lshl_add_u32 v145, v162, 13, v160
	v_add_u32_e32 v156, 0x20000, v145
	v_add_u32_e32 v158, 0x40000, v145
	v_add_u32_e32 v159, 0x60000, v145
	v_add_u32_e32 v176, 0x100000, v145
	v_add_u32_e32 v177, 0x120000, v145
	v_add_u32_e32 v223, 0x140000, v145
	v_add_u32_e32 v248, 0x160000, v145
	global_load_dwordx4 v[164:167], v145, s[82:83]
	global_load_dwordx4 v[168:171], v145, s[82:83] offset:64
	global_load_dwordx4 v[172:175], v145, s[82:83] offset:512
	global_load_dwordx4 v[180:183], v145, s[82:83] offset:576
	global_load_dwordx4 v[184:187], v156, s[82:83]
	global_load_dwordx4 v[188:191], v156, s[82:83] offset:64
	global_load_dwordx4 v[192:195], v156, s[82:83] offset:512
	global_load_dwordx4 v[196:199], v156, s[82:83] offset:576
	global_load_dwordx4 v[204:207], v158, s[82:83]
	global_load_dwordx4 v[212:215], v158, s[82:83] offset:64
	global_load_dwordx4 v[224:227], v158, s[82:83] offset:512
	global_load_dwordx4 v[228:231], v158, s[82:83] offset:576
	global_load_dwordx4 v[232:235], v159, s[82:83]
	global_load_dwordx4 v[236:239], v159, s[82:83] offset:64
	global_load_dwordx4 v[240:243], v159, s[82:83] offset:512
	global_load_dwordx4 v[244:247], v159, s[82:83] offset:576
	s_waitcnt vmcnt(15)
	v_pk_fma_f32 v[142:143], v[142:143], v[78:79], v[166:167]
	v_pk_fma_f32 v[140:141], v[140:141], v[76:77], v[164:165]
	global_store_dwordx4 v145, v[140:143], s[82:83]
	global_load_dwordx4 v[164:167], v176, s[82:83]
	s_waitcnt vmcnt(16)
	v_pk_fma_f32 v[138:139], v[138:139], v[74:75], v[170:171]
	v_pk_fma_f32 v[136:137], v[136:137], v[72:73], v[168:169]
	global_store_dwordx4 v145, v[136:139], s[82:83] offset:64
	global_load_dwordx4 v[168:171], v176, s[82:83] offset:64
	s_waitcnt vmcnt(17)
	v_pk_fma_f32 v[134:135], v[134:135], v[70:71], v[174:175]
	v_pk_fma_f32 v[132:133], v[132:133], v[68:69], v[172:173]
	global_store_dwordx4 v145, v[132:135], s[82:83] offset:512
	global_load_dwordx4 v[172:175], v176, s[82:83] offset:512
	s_waitcnt vmcnt(18)
	v_pk_fma_f32 v[130:131], v[130:131], v[50:51], v[182:183]
	v_pk_fma_f32 v[128:129], v[128:129], v[48:49], v[180:181]
	global_store_dwordx4 v145, v[128:131], s[82:83] offset:576
	global_load_dwordx4 v[180:183], v176, s[82:83] offset:576
	s_waitcnt vmcnt(19)
	v_pk_fma_f32 v[126:127], v[126:127], v[78:79], v[186:187]
	v_pk_fma_f32 v[124:125], v[124:125], v[76:77], v[184:185]
	global_store_dwordx4 v156, v[124:127], s[82:83]
	global_load_dwordx4 v[184:187], v177, s[82:83]
	s_waitcnt vmcnt(20)
	v_pk_fma_f32 v[122:123], v[122:123], v[74:75], v[190:191]
	v_pk_fma_f32 v[120:121], v[120:121], v[72:73], v[188:189]
	global_store_dwordx4 v156, v[120:123], s[82:83] offset:64
	global_load_dwordx4 v[188:191], v177, s[82:83] offset:64
	s_waitcnt vmcnt(21)
	v_pk_fma_f32 v[110:111], v[110:111], v[70:71], v[194:195]
	v_pk_fma_f32 v[108:109], v[108:109], v[68:69], v[192:193]
	global_store_dwordx4 v156, v[108:111], s[82:83] offset:512
	global_load_dwordx4 v[192:195], v177, s[82:83] offset:512
	s_waitcnt vmcnt(22)
	v_pk_fma_f32 v[106:107], v[106:107], v[50:51], v[198:199]
	v_pk_fma_f32 v[104:105], v[104:105], v[48:49], v[196:197]
	global_store_dwordx4 v156, v[104:107], s[82:83] offset:576
	global_load_dwordx4 v[196:199], v177, s[82:83] offset:576
	s_waitcnt vmcnt(23)
	v_pk_fma_f32 v[118:119], v[118:119], v[78:79], v[206:207]
	v_pk_fma_f32 v[116:117], v[116:117], v[76:77], v[204:205]
	global_store_dwordx4 v158, v[116:119], s[82:83]
	global_load_dwordx4 v[204:207], v223, s[82:83]
	s_waitcnt vmcnt(24)
	v_pk_fma_f32 v[114:115], v[114:115], v[74:75], v[214:215]
	v_pk_fma_f32 v[112:113], v[112:113], v[72:73], v[212:213]
	global_store_dwordx4 v158, v[112:115], s[82:83] offset:64
	global_load_dwordx4 v[212:215], v223, s[82:83] offset:64
	s_waitcnt vmcnt(25)
	v_pk_fma_f32 v[94:95], v[94:95], v[70:71], v[226:227]
	v_pk_fma_f32 v[92:93], v[92:93], v[68:69], v[224:225]
	global_store_dwordx4 v158, v[92:95], s[82:83] offset:512
	global_load_dwordx4 v[224:227], v223, s[82:83] offset:512
	s_waitcnt vmcnt(26)
	v_pk_fma_f32 v[90:91], v[90:91], v[50:51], v[230:231]
	v_pk_fma_f32 v[88:89], v[88:89], v[48:49], v[228:229]
	global_store_dwordx4 v158, v[88:91], s[82:83] offset:576
	global_load_dwordx4 v[228:231], v223, s[82:83] offset:576
	s_waitcnt vmcnt(27)
	v_pk_fma_f32 v[102:103], v[102:103], v[78:79], v[234:235]
	v_pk_fma_f32 v[100:101], v[100:101], v[76:77], v[232:233]
	global_store_dwordx4 v159, v[100:103], s[82:83]
	global_load_dwordx4 v[232:235], v248, s[82:83]
	s_waitcnt vmcnt(28)
	v_pk_fma_f32 v[98:99], v[98:99], v[74:75], v[238:239]
	v_pk_fma_f32 v[96:97], v[96:97], v[72:73], v[236:237]
	global_store_dwordx4 v159, v[96:99], s[82:83] offset:64
	global_load_dwordx4 v[236:239], v248, s[82:83] offset:64
	s_waitcnt vmcnt(29)
	v_pk_fma_f32 v[86:87], v[86:87], v[70:71], v[242:243]
	v_pk_fma_f32 v[84:85], v[84:85], v[68:69], v[240:241]
	global_store_dwordx4 v159, v[84:87], s[82:83] offset:512
	global_load_dwordx4 v[240:243], v248, s[82:83] offset:512
	s_waitcnt vmcnt(30)
	v_pk_fma_f32 v[82:83], v[82:83], v[50:51], v[246:247]
	v_pk_fma_f32 v[80:81], v[80:81], v[48:49], v[244:245]
	global_store_dwordx4 v159, v[80:83], s[82:83] offset:576
	global_load_dwordx4 v[244:247], v248, s[82:83] offset:576
	s_waitcnt vmcnt(30)
	v_pk_fma_f32 v[66:67], v[66:67], v[78:79], v[166:167]
	v_pk_fma_f32 v[64:65], v[64:65], v[76:77], v[164:165]
	global_store_dwordx4 v176, v[64:67], s[82:83]
	s_waitcnt vmcnt(29)
	v_pk_fma_f32 v[62:63], v[62:63], v[74:75], v[170:171]
	v_pk_fma_f32 v[60:61], v[60:61], v[72:73], v[168:169]
	global_store_dwordx4 v176, v[60:63], s[82:83] offset:64
	s_waitcnt vmcnt(28)
	v_pk_fma_f32 v[58:59], v[58:59], v[70:71], v[174:175]
	v_pk_fma_f32 v[56:57], v[56:57], v[68:69], v[172:173]
	global_store_dwordx4 v176, v[56:59], s[82:83] offset:512
	s_waitcnt vmcnt(27)
	v_pk_fma_f32 v[54:55], v[54:55], v[50:51], v[182:183]
	v_pk_fma_f32 v[52:53], v[52:53], v[48:49], v[180:181]
	global_store_dwordx4 v176, v[52:55], s[82:83] offset:576
	s_waitcnt vmcnt(26)
	v_pk_fma_f32 v[46:47], v[46:47], v[78:79], v[186:187]
	v_pk_fma_f32 v[44:45], v[44:45], v[76:77], v[184:185]
	global_store_dwordx4 v177, v[44:47], s[82:83]
	s_waitcnt vmcnt(25)
	v_pk_fma_f32 v[42:43], v[42:43], v[74:75], v[190:191]
	v_pk_fma_f32 v[40:41], v[40:41], v[72:73], v[188:189]
	global_store_dwordx4 v177, v[40:43], s[82:83] offset:64
	s_waitcnt vmcnt(24)
	v_pk_fma_f32 v[38:39], v[38:39], v[70:71], v[194:195]
	v_pk_fma_f32 v[36:37], v[36:37], v[68:69], v[192:193]
	global_store_dwordx4 v177, v[36:39], s[82:83] offset:512
	s_waitcnt vmcnt(23)
	v_pk_fma_f32 v[34:35], v[34:35], v[50:51], v[198:199]
	v_pk_fma_f32 v[32:33], v[32:33], v[48:49], v[196:197]
	global_store_dwordx4 v177, v[32:35], s[82:83] offset:576
	s_waitcnt vmcnt(22)
	v_pk_fma_f32 v[30:31], v[30:31], v[78:79], v[206:207]
	v_pk_fma_f32 v[28:29], v[28:29], v[76:77], v[204:205]
	global_store_dwordx4 v223, v[28:31], s[82:83]
	s_waitcnt vmcnt(21)
	v_pk_fma_f32 v[26:27], v[26:27], v[74:75], v[214:215]
	v_pk_fma_f32 v[24:25], v[24:25], v[72:73], v[212:213]
	global_store_dwordx4 v223, v[24:27], s[82:83] offset:64
	s_waitcnt vmcnt(20)
	v_pk_fma_f32 v[22:23], v[22:23], v[70:71], v[226:227]
	v_pk_fma_f32 v[20:21], v[20:21], v[68:69], v[224:225]
	global_store_dwordx4 v223, v[20:23], s[82:83] offset:512
	s_waitcnt vmcnt(19)
	v_pk_fma_f32 v[18:19], v[18:19], v[50:51], v[230:231]
	v_pk_fma_f32 v[16:17], v[16:17], v[48:49], v[228:229]
	global_store_dwordx4 v223, v[16:19], s[82:83] offset:576
	s_waitcnt vmcnt(18)
	v_pk_fma_f32 v[14:15], v[14:15], v[78:79], v[234:235]
	v_pk_fma_f32 v[12:13], v[12:13], v[76:77], v[232:233]
	global_store_dwordx4 v248, v[12:15], s[82:83]
	s_waitcnt vmcnt(17)
	v_pk_fma_f32 v[10:11], v[10:11], v[74:75], v[238:239]
	v_pk_fma_f32 v[8:9], v[8:9], v[72:73], v[236:237]
	global_store_dwordx4 v248, v[8:11], s[82:83] offset:64
	s_waitcnt vmcnt(16)
	v_pk_fma_f32 v[6:7], v[6:7], v[70:71], v[242:243]
	v_pk_fma_f32 v[4:5], v[4:5], v[68:69], v[240:241]
	global_store_dwordx4 v248, v[4:7], s[82:83] offset:512
	s_waitcnt vmcnt(15)
	v_pk_fma_f32 v[2:3], v[2:3], v[50:51], v[246:247]
	v_pk_fma_f32 v[0:1], v[0:1], v[48:49], v[244:245]
	global_store_dwordx4 v248, v[0:3], s[82:83] offset:576
	s_mov_b64 s[10:11], 0x160000
	s_cbranch_vccz .LBB0_1360
	s_waitcnt vmcnt(0)
	s_mov_b32 s4, s86
	s_cmp_gt_u32 s4, 3
	s_movk_i32 s57, 0x404
	s_cbranch_scc1 .LBB0_1367
	s_barrier
